# X25: GEMM MMA segments as 16 back-to-back accumulate chains in snake order over the 4x4 (A row tile, B col tile) grid
# speedup vs baseline: 1.0212x; 1.0071x over previous
; #define PG8_STAGE(bufoff, gbase, voff) do { _Pragma("unroll") for (int _i = 0; _i < 2; ++_i) \
;         __builtin_amdgcn_global_load_lds((const unsigned*)((const char*)(gbase) + (voff)[_i]), (PG8_LAS unsigned*)(lds + (bufoff) + ldsw + _i * 8192), 16, 0, 0); } while (0)
; #define PG8_LDA(dst, b, h) do { _Pragma("unroll") for (int m = 0; m < 4; ++m) _Pragma("unroll") for (int k = 0; k < 2; ++k) dst[m][k] = *(const PG8_LAS bf16x8*)(lds + PG8_SA(b, h) + aoff + m * 2048 + k * 1024); } while (0)
; #define PG8_LDB(dst, b, h) do { _Pragma("unroll") for (int n = 0; n < 2; ++n) _Pragma("unroll") for (int k = 0; k < 2; ++k) dst[n][k] = *(const PG8_LAS bf16x8*)(lds + PG8_SB(b, h) + boff + n * 2048 + k * 1024); } while (0)
; #define PG8_MMA(ai, bj, At, Bt) do { __builtin_amdgcn_s_setprio(1); _Pragma("unroll") for (int m = 0; m < 4; ++m) _Pragma("unroll") for (int n = 0; n < 2; ++n) _Pragma("unroll") for (int k = 0; k < 2; ++k) \
;         acc[ai][bj][m][n] = __builtin_amdgcn_mfma_f32_16x16x32_bf16(Bt[n][k], At[m][k], acc[ai][bj][m][n], 0, 0, 0); __builtin_amdgcn_s_setprio(0); } while (0)
; #define PG8_WAIT_V(n) asm volatile("s_waitcnt vmcnt(" #n ")" ::: "memory")
; #define PG8_WAIT_L(n) asm volatile("s_waitcnt lgkmcnt(" #n ")" ::: "memory")
; #define PG8_BAR __builtin_amdgcn_s_barrier()
; #define PG8_SCHED __builtin_amdgcn_sched_barrier(0)
; template <class Epi, class Sched, bool ALIGN_EPI = false, bool SP2 = false>
; __device__ __forceinline__ void gemm_phase(PG8_LAS unsigned char* lds, const Gemm g, const Sched& S, const Epi& E) {
;     ...
;             const bool last = (t == nt - 2);
;             const char* a1 = cA + (size_t)(t + 1) * kstep;
;             const char* a2 = last ? nA : cA + (size_t)(t + 2) * kstep; const char* b2 = last ? nB : cB + (size_t)(t + 2) * kstep;
;             const char* a3 = a2 + kstep; const char* b3 = b2 + kstep;
;             if (last && has_next) S.a_ready(nxt);
;             if constexpr (SP2) {
;             PG8_LDB(B0, 0, 0); PG8_LDB(B1, 0, 1); PG8_SCHED; PG8_LDA(At, 0, 0); PG8_STAGE(PG8_SA(1, 1), a1 + hstep, voffA);
;             PG8_WAIT_V(8); PG8_WAIT_L(0); PG8_BAR; PG8_MMA(0, 0, At, B0); PG8_MMA(0, 1, At, B1); PG8_BAR; PG8_SCHED;
;             PG8_LDA(At, 0, 1); PG8_STAGE(PG8_SB(0, 0), b2, voffB); PG8_STAGE(PG8_SB(0, 1), b2 + hstep, voffB); PG8_STAGE(PG8_SA(0, 0), a2, voffA);
.LBB0_216:
	s_add_u32 s22, s54, 0xfff80080
	s_addc_u32 s23, s55, -1
	s_add_i32 s34, 0, 0x10000
	s_cmp_eq_u32 s20, 28
	s_cselect_b32 s57, s47, s23
	s_cselect_b32 s56, vcc_lo, s22
	v_add_u32_e32 v152, s34, v155
	s_cselect_b32 s23, s49, s77
	s_cselect_b32 s22, vcc_hi, s71
	s_add_i32 s4, 0, 0x14000
	ds_read_b128 v[144:147], v152
	ds_read_b128 v[148:151], v152 offset:1024
	ds_read_b128 v[168:171], v152 offset:2048
	ds_read_b128 v[172:175], v152 offset:3072
	v_add_u32_e32 v152, s4, v155
	ds_read_b128 v[176:179], v152
	ds_read_b128 v[180:183], v152 offset:1024
	ds_read_b128 v[184:187], v152 offset:2048
	ds_read_b128 v[188:191], v152 offset:3072
	v_lshl_add_u64 v[152:153], s[54:55], 0, v[140:141]
	s_add_i32 m0, s66, 0xc000
	ds_read_b128 v[212:215], v157
	ds_read_b128 v[216:219], v157 offset:1024
	ds_read_b128 v[220:223], v157 offset:2048
	ds_read_b128 v[224:227], v157 offset:3072
	ds_read_b128 v[228:231], v157 offset:4096
	ds_read_b128 v[232:235], v157 offset:5120
	ds_read_b128 v[236:239], v157 offset:6144
	ds_read_b128 v[240:243], v157 offset:7168
	global_load_lds_dwordx4 v[152:153], off
	v_lshl_add_u64 v[152:153], s[54:55], 0, v[142:143]
	s_add_i32 m0, s66, 0xe000
	s_nop 0
	global_load_lds_dwordx4 v[152:153], off
	s_waitcnt vmcnt(8)
	s_waitcnt lgkmcnt(0)
	s_barrier
	v_mfma_f32_16x16x32_bf16 v[126:129], v[144:147], v[212:215], v[126:129]
	v_mfma_f32_16x16x32_bf16 v[126:129], v[148:151], v[216:219], v[126:129]
	v_mfma_f32_16x16x32_bf16 v[118:121], v[168:171], v[212:215], v[118:121]
	v_mfma_f32_16x16x32_bf16 v[118:121], v[172:175], v[216:219], v[118:121]
	v_mfma_f32_16x16x32_bf16 v[130:133], v[176:179], v[212:215], v[130:133]
	v_mfma_f32_16x16x32_bf16 v[130:133], v[180:183], v[216:219], v[130:133]
	v_mfma_f32_16x16x32_bf16 v[122:125], v[184:187], v[212:215], v[122:125]
	v_mfma_f32_16x16x32_bf16 v[122:125], v[188:191], v[216:219], v[122:125]
	v_mfma_f32_16x16x32_bf16 v[106:109], v[184:187], v[220:223], v[106:109]
	v_mfma_f32_16x16x32_bf16 v[106:109], v[188:191], v[224:227], v[106:109]
	v_mfma_f32_16x16x32_bf16 v[114:117], v[176:179], v[220:223], v[114:117]
	v_mfma_f32_16x16x32_bf16 v[114:117], v[180:183], v[224:227], v[114:117]
	v_mfma_f32_16x16x32_bf16 v[102:105], v[168:171], v[220:223], v[102:105]
	v_mfma_f32_16x16x32_bf16 v[102:105], v[172:175], v[224:227], v[102:105]
	v_mfma_f32_16x16x32_bf16 v[110:113], v[144:147], v[220:223], v[110:113]
	v_mfma_f32_16x16x32_bf16 v[110:113], v[148:151], v[224:227], v[110:113]
	v_mfma_f32_16x16x32_bf16 v[94:97], v[144:147], v[228:231], v[94:97]
	v_mfma_f32_16x16x32_bf16 v[94:97], v[148:151], v[232:235], v[94:97]
	v_mfma_f32_16x16x32_bf16 v[86:89], v[168:171], v[228:231], v[86:89]
	v_mfma_f32_16x16x32_bf16 v[86:89], v[172:175], v[232:235], v[86:89]
	v_mfma_f32_16x16x32_bf16 v[98:101], v[176:179], v[228:231], v[98:101]
	v_mfma_f32_16x16x32_bf16 v[98:101], v[180:183], v[232:235], v[98:101]
	v_mfma_f32_16x16x32_bf16 v[90:93], v[184:187], v[228:231], v[90:93]
	v_mfma_f32_16x16x32_bf16 v[90:93], v[188:191], v[232:235], v[90:93]
	v_mfma_f32_16x16x32_bf16 v[74:77], v[184:187], v[236:239], v[74:77]
	v_mfma_f32_16x16x32_bf16 v[74:77], v[188:191], v[240:243], v[74:77]
	v_mfma_f32_16x16x32_bf16 v[82:85], v[176:179], v[236:239], v[82:85]
	v_mfma_f32_16x16x32_bf16 v[82:85], v[180:183], v[240:243], v[82:85]
	v_mfma_f32_16x16x32_bf16 v[70:73], v[168:171], v[236:239], v[70:73]
	v_mfma_f32_16x16x32_bf16 v[70:73], v[172:175], v[240:243], v[70:73]
	v_mfma_f32_16x16x32_bf16 v[78:81], v[144:147], v[236:239], v[78:81]
	v_mfma_f32_16x16x32_bf16 v[78:81], v[148:151], v[240:243], v[78:81]
	s_barrier
	s_add_i32 s5, s34, s65
	v_lshl_add_u64 v[152:153], s[22:23], 0, v[4:5]
	s_mov_b32 m0, s5
	ds_read_b128 v[212:215], v157 offset:16384
	ds_read_b128 v[216:219], v157 offset:17408
	ds_read_b128 v[220:223], v157 offset:18432
	ds_read_b128 v[224:227], v157 offset:19456
	ds_read_b128 v[228:231], v157 offset:20480
	ds_read_b128 v[232:235], v157 offset:21504
	ds_read_b128 v[236:239], v157 offset:22528
	ds_read_b128 v[240:243], v157 offset:23552
	global_load_lds_dwordx4 v[152:153], off
	s_add_i32 m0, s5, 0x2000
	s_add_u32 s34, s22, 0x80000
	v_lshl_add_u64 v[192:193], s[22:23], 0, v[2:3]
	s_addc_u32 s35, s23, 0
	s_add_i32 s4, s4, s65
	global_load_lds_dwordx4 v[192:193], off
	v_lshl_add_u64 v[244:245], s[34:35], 0, v[4:5]
	s_mov_b32 m0, s4
	v_lshl_add_u64 v[246:247], s[56:57], 0, v[134:135]
	global_load_lds_dwordx4 v[244:245], off
	v_lshl_add_u64 v[244:245], s[34:35], 0, v[2:3]
	s_add_i32 m0, s4, 0x2000
	s_nop 0
	global_load_lds_dwordx4 v[244:245], off
	v_lshl_add_u64 v[244:245], s[56:57], 0, v[136:137]
	s_mov_b32 m0, s66
	s_nop 0
	global_load_lds_dwordx4 v[244:245], off
	s_mov_b32 m0, s67
	s_nop 0
	global_load_lds_dwordx4 v[246:247], off
	s_waitcnt vmcnt(8)
	s_waitcnt lgkmcnt(0)
	s_barrier
; #define PG8_STAGE(bufoff, gbase, voff) do { _Pragma("unroll") for (int _i = 0; _i < 2; ++_i) \
;         __builtin_amdgcn_global_load_lds((const unsigned*)((const char*)(gbase) + (voff)[_i]), (PG8_LAS unsigned*)(lds + (bufoff) + ldsw + _i * 8192), 16, 0, 0); } while (0)
; #define PG8_LDA(dst, b, h) do { _Pragma("unroll") for (int m = 0; m < 4; ++m) _Pragma("unroll") for (int k = 0; k < 2; ++k) dst[m][k] = *(const PG8_LAS bf16x8*)(lds + PG8_SA(b, h) + aoff + m * 2048 + k * 1024); } while (0)
; #define PG8_LDB(dst, b, h) do { _Pragma("unroll") for (int n = 0; n < 2; ++n) _Pragma("unroll") for (int k = 0; k < 2; ++k) dst[n][k] = *(const PG8_LAS bf16x8*)(lds + PG8_SB(b, h) + boff + n * 2048 + k * 1024); } while (0)
; #define PG8_MMA(ai, bj, At, Bt) do { __builtin_amdgcn_s_setprio(1); _Pragma("unroll") for (int m = 0; m < 4; ++m) _Pragma("unroll") for (int n = 0; n < 2; ++n) _Pragma("unroll") for (int k = 0; k < 2; ++k) \
;         acc[ai][bj][m][n] = __builtin_amdgcn_mfma_f32_16x16x32_bf16(Bt[n][k], At[m][k], acc[ai][bj][m][n], 0, 0, 0); __builtin_amdgcn_s_setprio(0); } while (0)
; #define PG8_WAIT_V(n) asm volatile("s_waitcnt vmcnt(" #n ")" ::: "memory")
; #define PG8_WAIT_L(n) asm volatile("s_waitcnt lgkmcnt(" #n ")" ::: "memory")
; #define PG8_BAR __builtin_amdgcn_s_barrier()
; #define PG8_SCHED __builtin_amdgcn_sched_barrier(0)
; template <class Epi, class Sched, bool ALIGN_EPI = false, bool SP2 = false>
; __device__ __forceinline__ void gemm_phase(PG8_LAS unsigned char* lds, const Gemm g, const Sched& S, const Epi& E) {
;     ...
;             PG8_WAIT_V(8); PG8_WAIT_L(0); PG8_BAR; PG8_MMA(1, 0, At, B0); PG8_MMA(1, 1, At, B1); PG8_BAR; PG8_SCHED;
;             PG8_LDB(B0, 1, 0); PG8_LDB(B1, 1, 1); PG8_SCHED; PG8_LDA(At, 1, 0); PG8_STAGE(PG8_SA(0, 1), a2 + hstep, voffA);
;             PG8_WAIT_V(8); PG8_WAIT_L(0); PG8_BAR; PG8_MMA(0, 0, At, B0); PG8_MMA(0, 1, At, B1); PG8_BAR; PG8_SCHED;
	v_mfma_f32_16x16x32_bf16 v[62:65], v[144:147], v[212:215], v[62:65]
	v_mfma_f32_16x16x32_bf16 v[62:65], v[148:151], v[216:219], v[62:65]
	v_mfma_f32_16x16x32_bf16 v[54:57], v[168:171], v[212:215], v[54:57]
	v_mfma_f32_16x16x32_bf16 v[54:57], v[172:175], v[216:219], v[54:57]
	v_mfma_f32_16x16x32_bf16 v[66:69], v[176:179], v[212:215], v[66:69]
	v_mfma_f32_16x16x32_bf16 v[66:69], v[180:183], v[216:219], v[66:69]
	v_mfma_f32_16x16x32_bf16 v[58:61], v[184:187], v[212:215], v[58:61]
	v_mfma_f32_16x16x32_bf16 v[58:61], v[188:191], v[216:219], v[58:61]
	v_mfma_f32_16x16x32_bf16 v[42:45], v[184:187], v[220:223], v[42:45]
	v_mfma_f32_16x16x32_bf16 v[42:45], v[188:191], v[224:227], v[42:45]
	v_mfma_f32_16x16x32_bf16 v[50:53], v[176:179], v[220:223], v[50:53]
	v_mfma_f32_16x16x32_bf16 v[50:53], v[180:183], v[224:227], v[50:53]
	v_mfma_f32_16x16x32_bf16 v[38:41], v[168:171], v[220:223], v[38:41]
	v_mfma_f32_16x16x32_bf16 v[38:41], v[172:175], v[224:227], v[38:41]
	v_mfma_f32_16x16x32_bf16 v[46:49], v[144:147], v[220:223], v[46:49]
	v_mfma_f32_16x16x32_bf16 v[46:49], v[148:151], v[224:227], v[46:49]
	v_mfma_f32_16x16x32_bf16 v[30:33], v[144:147], v[228:231], v[30:33]
	v_mfma_f32_16x16x32_bf16 v[30:33], v[148:151], v[232:235], v[30:33]
	v_mfma_f32_16x16x32_bf16 v[22:25], v[168:171], v[228:231], v[22:25]
	v_mfma_f32_16x16x32_bf16 v[22:25], v[172:175], v[232:235], v[22:25]
	v_mfma_f32_16x16x32_bf16 v[34:37], v[176:179], v[228:231], v[34:37]
	v_mfma_f32_16x16x32_bf16 v[34:37], v[180:183], v[232:235], v[34:37]
	v_mfma_f32_16x16x32_bf16 v[26:29], v[184:187], v[228:231], v[26:29]
	v_mfma_f32_16x16x32_bf16 v[26:29], v[188:191], v[232:235], v[26:29]
	v_mfma_f32_16x16x32_bf16 v[10:13], v[184:187], v[236:239], v[10:13]
	v_mfma_f32_16x16x32_bf16 v[10:13], v[188:191], v[240:243], v[10:13]
	v_mfma_f32_16x16x32_bf16 v[18:21], v[176:179], v[236:239], v[18:21]
	v_mfma_f32_16x16x32_bf16 v[18:21], v[180:183], v[240:243], v[18:21]
	v_mfma_f32_16x16x32_bf16 v[6:9], v[168:171], v[236:239], v[6:9]
	v_mfma_f32_16x16x32_bf16 v[6:9], v[172:175], v[240:243], v[6:9]
	v_mfma_f32_16x16x32_bf16 v[14:17], v[144:147], v[236:239], v[14:17]
	v_mfma_f32_16x16x32_bf16 v[14:17], v[148:151], v[240:243], v[14:17]
	s_barrier
	s_add_i32 s4, 0, 0x18000
	v_add_u32_e32 v158, s4, v155
	s_add_i32 s5, 0, 0x1c000
	ds_read_b128 v[144:147], v158
	ds_read_b128 v[148:151], v158 offset:1024
	ds_read_b128 v[168:171], v158 offset:2048
	ds_read_b128 v[172:175], v158 offset:3072
	v_add_u32_e32 v158, s5, v155
	ds_read_b128 v[176:179], v158
	ds_read_b128 v[180:183], v158 offset:1024
	ds_read_b128 v[184:187], v158 offset:2048
	ds_read_b128 v[188:191], v158 offset:3072
	s_add_u32 s34, s56, 0x80000
	s_addc_u32 s35, s57, 0
	s_mov_b32 m0, s60
	v_lshl_add_u64 v[248:249], s[34:35], 0, v[136:137]
	ds_read_b128 v[212:215], v157 offset:32768
	ds_read_b128 v[216:219], v157 offset:33792
	ds_read_b128 v[220:223], v157 offset:34816
	ds_read_b128 v[224:227], v157 offset:35840
	ds_read_b128 v[228:231], v157 offset:36864
	ds_read_b128 v[232:235], v157 offset:37888
	ds_read_b128 v[236:239], v157 offset:38912
	ds_read_b128 v[240:243], v157 offset:39936
	global_load_lds_dwordx4 v[248:249], off
	v_lshl_add_u64 v[248:249], s[34:35], 0, v[134:135]
	s_mov_b32 m0, s2
	s_nop 0
	global_load_lds_dwordx4 v[248:249], off
	s_waitcnt vmcnt(8)
	s_waitcnt lgkmcnt(0)
	s_barrier
	v_mfma_f32_16x16x32_bf16 v[126:129], v[144:147], v[212:215], v[126:129]
	v_mfma_f32_16x16x32_bf16 v[126:129], v[148:151], v[216:219], v[126:129]
	v_mfma_f32_16x16x32_bf16 v[118:121], v[168:171], v[212:215], v[118:121]
	v_mfma_f32_16x16x32_bf16 v[118:121], v[172:175], v[216:219], v[118:121]
	v_mfma_f32_16x16x32_bf16 v[130:133], v[176:179], v[212:215], v[130:133]
	v_mfma_f32_16x16x32_bf16 v[130:133], v[180:183], v[216:219], v[130:133]
	v_mfma_f32_16x16x32_bf16 v[122:125], v[184:187], v[212:215], v[122:125]
	v_mfma_f32_16x16x32_bf16 v[122:125], v[188:191], v[216:219], v[122:125]
	v_mfma_f32_16x16x32_bf16 v[106:109], v[184:187], v[220:223], v[106:109]
	v_mfma_f32_16x16x32_bf16 v[106:109], v[188:191], v[224:227], v[106:109]
	v_mfma_f32_16x16x32_bf16 v[114:117], v[176:179], v[220:223], v[114:117]
	v_mfma_f32_16x16x32_bf16 v[114:117], v[180:183], v[224:227], v[114:117]
	v_mfma_f32_16x16x32_bf16 v[102:105], v[168:171], v[220:223], v[102:105]
	v_mfma_f32_16x16x32_bf16 v[102:105], v[172:175], v[224:227], v[102:105]
	v_mfma_f32_16x16x32_bf16 v[110:113], v[144:147], v[220:223], v[110:113]
	v_mfma_f32_16x16x32_bf16 v[110:113], v[148:151], v[224:227], v[110:113]
	v_mfma_f32_16x16x32_bf16 v[94:97], v[144:147], v[228:231], v[94:97]
	v_mfma_f32_16x16x32_bf16 v[94:97], v[148:151], v[232:235], v[94:97]
	v_mfma_f32_16x16x32_bf16 v[86:89], v[168:171], v[228:231], v[86:89]
	v_mfma_f32_16x16x32_bf16 v[86:89], v[172:175], v[232:235], v[86:89]
	v_mfma_f32_16x16x32_bf16 v[98:101], v[176:179], v[228:231], v[98:101]
	v_mfma_f32_16x16x32_bf16 v[98:101], v[180:183], v[232:235], v[98:101]
	v_mfma_f32_16x16x32_bf16 v[90:93], v[184:187], v[228:231], v[90:93]
	v_mfma_f32_16x16x32_bf16 v[90:93], v[188:191], v[232:235], v[90:93]
	v_mfma_f32_16x16x32_bf16 v[74:77], v[184:187], v[236:239], v[74:77]
	v_mfma_f32_16x16x32_bf16 v[74:77], v[188:191], v[240:243], v[74:77]
	v_mfma_f32_16x16x32_bf16 v[82:85], v[176:179], v[236:239], v[82:85]
	v_mfma_f32_16x16x32_bf16 v[82:85], v[180:183], v[240:243], v[82:85]
	v_mfma_f32_16x16x32_bf16 v[70:73], v[168:171], v[236:239], v[70:73]
	v_mfma_f32_16x16x32_bf16 v[70:73], v[172:175], v[240:243], v[70:73]
	v_mfma_f32_16x16x32_bf16 v[78:81], v[144:147], v[236:239], v[78:81]
	v_mfma_f32_16x16x32_bf16 v[78:81], v[148:151], v[240:243], v[78:81]
	s_barrier
; #define PG8_STAGE(bufoff, gbase, voff) do { _Pragma("unroll") for (int _i = 0; _i < 2; ++_i) \
;         __builtin_amdgcn_global_load_lds((const unsigned*)((const char*)(gbase) + (voff)[_i]), (PG8_LAS unsigned*)(lds + (bufoff) + ldsw + _i * 8192), 16, 0, 0); } while (0)
; #define PG8_LDA(dst, b, h) do { _Pragma("unroll") for (int m = 0; m < 4; ++m) _Pragma("unroll") for (int k = 0; k < 2; ++k) dst[m][k] = *(const PG8_LAS bf16x8*)(lds + PG8_SA(b, h) + aoff + m * 2048 + k * 1024); } while (0)
; #define PG8_MMA(ai, bj, At, Bt) do { __builtin_amdgcn_s_setprio(1); _Pragma("unroll") for (int m = 0; m < 4; ++m) _Pragma("unroll") for (int n = 0; n < 2; ++n) _Pragma("unroll") for (int k = 0; k < 2; ++k) \
;         acc[ai][bj][m][n] = __builtin_amdgcn_mfma_f32_16x16x32_bf16(Bt[n][k], At[m][k], acc[ai][bj][m][n], 0, 0, 0); __builtin_amdgcn_s_setprio(0); } while (0)
; #define PG8_WAIT_V(n) asm volatile("s_waitcnt vmcnt(" #n ")" ::: "memory")
; #define PG8_WAIT_L(n) asm volatile("s_waitcnt lgkmcnt(" #n ")" ::: "memory")
; #define PG8_BAR __builtin_amdgcn_s_barrier()
; #define PG8_SCHED __builtin_amdgcn_sched_barrier(0)
; template <class Epi, class Sched, bool ALIGN_EPI = false, bool SP2 = false>
; __device__ __forceinline__ void gemm_phase(PG8_LAS unsigned char* lds, const Gemm g, const Sched& S, const Epi& E) {
;     ...
;         for (int t = 0; t < nt; t += 2) {
;     ...
;             PG8_LDA(At, 1, 1); PG8_STAGE(PG8_SB(1, 0), b3, voffB); PG8_STAGE(PG8_SB(1, 1), b3 + hstep, voffB); PG8_STAGE(PG8_SA(1, 0), a3, voffA);
;             PG8_WAIT_V(8); PG8_WAIT_L(0); PG8_BAR; PG8_MMA(1, 0, At, B0); PG8_MMA(1, 1, At, B1); PG8_BAR; PG8_SCHED;
	s_add_i32 s4, s4, s65
	v_lshl_add_u64 v[152:153], v[152:153], 0, s[28:29]
	s_mov_b32 m0, s4
	ds_read_b128 v[212:215], v157 offset:49152
	ds_read_b128 v[216:219], v157 offset:50176
	ds_read_b128 v[220:223], v157 offset:51200
	ds_read_b128 v[224:227], v157 offset:52224
	ds_read_b128 v[228:231], v157 offset:53248
	ds_read_b128 v[232:235], v157 offset:54272
	ds_read_b128 v[236:239], v157 offset:55296
	ds_read_b128 v[240:243], v157 offset:56320
	global_load_lds_dwordx4 v[152:153], off
	s_add_i32 m0, s4, 0x2000
	s_add_u32 s22, s22, 0x80080
	v_lshl_add_u64 v[152:153], v[192:193], 0, s[28:29]
	s_addc_u32 s23, s23, 0
	s_add_i32 s4, s5, s65
	global_load_lds_dwordx4 v[152:153], off
	v_lshl_add_u64 v[152:153], s[22:23], 0, v[4:5]
	s_mov_b32 m0, s4
	s_nop 0
	global_load_lds_dwordx4 v[152:153], off
	v_lshl_add_u64 v[152:153], s[22:23], 0, v[2:3]
	s_add_i32 m0, s4, 0x2000
	s_nop 0
	global_load_lds_dwordx4 v[152:153], off
	v_lshl_add_u64 v[152:153], v[244:245], 0, s[28:29]
	s_mov_b32 m0, s3
	s_nop 0
	global_load_lds_dwordx4 v[152:153], off
	v_lshl_add_u64 v[152:153], v[246:247], 0, s[28:29]
	s_mov_b32 m0, s75
	s_nop 0
	global_load_lds_dwordx4 v[152:153], off
	s_waitcnt vmcnt(8)
	s_waitcnt lgkmcnt(0)
	s_barrier
	v_mfma_f32_16x16x32_bf16 v[62:65], v[144:147], v[212:215], v[62:65]
	v_mfma_f32_16x16x32_bf16 v[62:65], v[148:151], v[216:219], v[62:65]
	v_mfma_f32_16x16x32_bf16 v[54:57], v[168:171], v[212:215], v[54:57]
	v_mfma_f32_16x16x32_bf16 v[54:57], v[172:175], v[216:219], v[54:57]
	v_mfma_f32_16x16x32_bf16 v[66:69], v[176:179], v[212:215], v[66:69]
	v_mfma_f32_16x16x32_bf16 v[66:69], v[180:183], v[216:219], v[66:69]
	v_mfma_f32_16x16x32_bf16 v[58:61], v[184:187], v[212:215], v[58:61]
	v_mfma_f32_16x16x32_bf16 v[58:61], v[188:191], v[216:219], v[58:61]
	v_mfma_f32_16x16x32_bf16 v[42:45], v[184:187], v[220:223], v[42:45]
	v_mfma_f32_16x16x32_bf16 v[42:45], v[188:191], v[224:227], v[42:45]
	v_mfma_f32_16x16x32_bf16 v[50:53], v[176:179], v[220:223], v[50:53]
	v_mfma_f32_16x16x32_bf16 v[50:53], v[180:183], v[224:227], v[50:53]
	v_mfma_f32_16x16x32_bf16 v[38:41], v[168:171], v[220:223], v[38:41]
	v_mfma_f32_16x16x32_bf16 v[38:41], v[172:175], v[224:227], v[38:41]
	v_mfma_f32_16x16x32_bf16 v[46:49], v[144:147], v[220:223], v[46:49]
	v_mfma_f32_16x16x32_bf16 v[46:49], v[148:151], v[224:227], v[46:49]
	v_mfma_f32_16x16x32_bf16 v[30:33], v[144:147], v[228:231], v[30:33]
	v_mfma_f32_16x16x32_bf16 v[30:33], v[148:151], v[232:235], v[30:33]
	v_mfma_f32_16x16x32_bf16 v[22:25], v[168:171], v[228:231], v[22:25]
	v_mfma_f32_16x16x32_bf16 v[22:25], v[172:175], v[232:235], v[22:25]
	v_mfma_f32_16x16x32_bf16 v[34:37], v[176:179], v[228:231], v[34:37]
	v_mfma_f32_16x16x32_bf16 v[34:37], v[180:183], v[232:235], v[34:37]
	v_mfma_f32_16x16x32_bf16 v[26:29], v[184:187], v[228:231], v[26:29]
	v_mfma_f32_16x16x32_bf16 v[26:29], v[188:191], v[232:235], v[26:29]
	v_mfma_f32_16x16x32_bf16 v[10:13], v[184:187], v[236:239], v[10:13]
	v_mfma_f32_16x16x32_bf16 v[10:13], v[188:191], v[240:243], v[10:13]
	v_mfma_f32_16x16x32_bf16 v[18:21], v[176:179], v[236:239], v[18:21]
	v_mfma_f32_16x16x32_bf16 v[18:21], v[180:183], v[240:243], v[18:21]
	v_mfma_f32_16x16x32_bf16 v[6:9], v[168:171], v[236:239], v[6:9]
	v_mfma_f32_16x16x32_bf16 v[6:9], v[172:175], v[240:243], v[6:9]
	v_mfma_f32_16x16x32_bf16 v[14:17], v[144:147], v[236:239], v[14:17]
	v_mfma_f32_16x16x32_bf16 v[14:17], v[148:151], v[240:243], v[14:17]
	s_barrier
	s_add_i32 s20, s20, 2
	s_add_u32 s54, s54, 0x100
	s_addc_u32 s55, s55, 0
	s_add_u32 s71, s71, 0x100
	s_addc_u32 s77, s77, 0
	s_cmp_gt_u32 s20, 29
	s_cbranch_scc0 .LBB0_216
	s_and_b64 vcc, exec, s[44:45]
	s_movk_i32 s77, 0x6000
	s_mov_b32 s71, 0x44800000
	s_cbranch_vccz .LBB0_219
	s_barrier

; #define PG8_STAGE(bufoff, gbase, voff) do { _Pragma("unroll") for (int _i = 0; _i < 2; ++_i) \
;         __builtin_amdgcn_global_load_lds((const unsigned*)((const char*)(gbase) + (voff)[_i]), (PG8_LAS unsigned*)(lds + (bufoff) + ldsw + _i * 8192), 16, 0, 0); } while (0)
; #define PG8_LDA(dst, b, h) do { _Pragma("unroll") for (int m = 0; m < 4; ++m) _Pragma("unroll") for (int k = 0; k < 2; ++k) dst[m][k] = *(const PG8_LAS bf16x8*)(lds + PG8_SA(b, h) + aoff + m * 2048 + k * 1024); } while (0)
; #define PG8_LDB(dst, b, h) do { _Pragma("unroll") for (int n = 0; n < 2; ++n) _Pragma("unroll") for (int k = 0; k < 2; ++k) dst[n][k] = *(const PG8_LAS bf16x8*)(lds + PG8_SB(b, h) + boff + n * 2048 + k * 1024); } while (0)
; #define PG8_MMA(ai, bj, At, Bt) do { __builtin_amdgcn_s_setprio(1); _Pragma("unroll") for (int m = 0; m < 4; ++m) _Pragma("unroll") for (int n = 0; n < 2; ++n) _Pragma("unroll") for (int k = 0; k < 2; ++k) \
;         acc[ai][bj][m][n] = __builtin_amdgcn_mfma_f32_16x16x32_bf16(Bt[n][k], At[m][k], acc[ai][bj][m][n], 0, 0, 0); __builtin_amdgcn_s_setprio(0); } while (0)
; #define PG8_WAIT_V(n) asm volatile("s_waitcnt vmcnt(" #n ")" ::: "memory")
; #define PG8_WAIT_L(n) asm volatile("s_waitcnt lgkmcnt(" #n ")" ::: "memory")
; #define PG8_BAR __builtin_amdgcn_s_barrier()
; #define PG8_SCHED __builtin_amdgcn_sched_barrier(0)
; template <class Epi, class Sched, bool ALIGN_EPI = false, bool SP2 = false>
; __device__ __forceinline__ void gemm_phase(PG8_LAS unsigned char* lds, const Gemm g, const Sched& S, const Epi& E) {
;     ...
;             const bool last = (t == nt - 2);
;             const char* a1 = cA + (size_t)(t + 1) * kstep;
;             const char* a2 = last ? nA : cA + (size_t)(t + 2) * kstep; const char* b2 = last ? nB : cB + (size_t)(t + 2) * kstep;
;             const char* a3 = a2 + kstep; const char* b3 = b2 + kstep;
;             if (last && has_next) S.a_ready(nxt);
;             if constexpr (SP2) {
;             PG8_LDB(B0, 0, 0); PG8_LDB(B1, 0, 1); PG8_SCHED; PG8_LDA(At, 0, 0); PG8_STAGE(PG8_SA(1, 1), a1 + hstep, voffA);
;             PG8_WAIT_V(8); PG8_WAIT_L(0); PG8_BAR; PG8_MMA(0, 0, At, B0); PG8_MMA(0, 1, At, B1); PG8_BAR; PG8_SCHED;
;             PG8_LDA(At, 0, 1); PG8_STAGE(PG8_SB(0, 0), b2, voffB); PG8_STAGE(PG8_SB(0, 1), b2 + hstep, voffB); PG8_STAGE(PG8_SA(0, 0), a2, voffA);
.LBB0_299:
	s_add_u32 s50, s22, 0x100
	s_addc_u32 s51, s23, 0
	s_add_i32 s4, 0, 0x10000
	s_cmpk_eq_i32 s20, 0x54
	s_cselect_b32 s55, s41, s51
	s_cselect_b32 s54, s40, s50
	s_cselect_b32 s53, s49, s69
	s_cselect_b32 s52, s48, s33
	s_add_i32 s5, 0, 0x14000
	v_add_u32_e32 v146, s4, v158
	v_add_u32_e32 v180, s5, v158
	ds_read_b128 v[134:137], v146
	ds_read_b128 v[138:141], v146 offset:1024
	ds_read_b128 v[142:145], v146 offset:2048
	ds_read_b128 v[146:149], v146 offset:3072
	ds_read_b128 v[150:153], v180
	ds_read_b128 v[154:157], v180 offset:1024
	ds_read_b128 v[176:179], v180 offset:2048
	ds_read_b128 v[180:183], v180 offset:3072
	v_lshl_add_u64 v[236:237], s[22:23], 0, v[172:173]
	s_add_i32 m0, s56, 0xc000
	ds_read_b128 v[184:187], v188
	ds_read_b128 v[190:193], v188 offset:1024
	ds_read_b128 v[212:215], v188 offset:2048
	ds_read_b128 v[216:219], v188 offset:3072
	ds_read_b128 v[220:223], v188 offset:4096
	ds_read_b128 v[224:227], v188 offset:5120
	ds_read_b128 v[228:231], v188 offset:6144
	ds_read_b128 v[232:235], v188 offset:7168
	global_load_lds_dwordx4 v[236:237], off
	v_lshl_add_u64 v[236:237], s[22:23], 0, v[174:175]
	s_add_i32 m0, s56, 0xe000
	s_nop 0
	global_load_lds_dwordx4 v[236:237], off
	s_waitcnt vmcnt(8)
	s_waitcnt lgkmcnt(0)
	s_barrier
	v_mfma_f32_16x16x32_bf16 v[122:125], v[134:137], v[184:187], v[122:125]
	v_mfma_f32_16x16x32_bf16 v[122:125], v[138:141], v[190:193], v[122:125]
	v_mfma_f32_16x16x32_bf16 v[118:121], v[142:145], v[184:187], v[118:121]
	v_mfma_f32_16x16x32_bf16 v[118:121], v[146:149], v[190:193], v[118:121]
	v_mfma_f32_16x16x32_bf16 v[130:133], v[150:153], v[184:187], v[130:133]
	v_mfma_f32_16x16x32_bf16 v[130:133], v[154:157], v[190:193], v[130:133]
	v_mfma_f32_16x16x32_bf16 v[126:129], v[176:179], v[184:187], v[126:129]
	v_mfma_f32_16x16x32_bf16 v[126:129], v[180:183], v[190:193], v[126:129]
	v_mfma_f32_16x16x32_bf16 v[102:105], v[176:179], v[212:215], v[102:105]
	v_mfma_f32_16x16x32_bf16 v[102:105], v[180:183], v[216:219], v[102:105]
	v_mfma_f32_16x16x32_bf16 v[106:109], v[150:153], v[212:215], v[106:109]
	v_mfma_f32_16x16x32_bf16 v[106:109], v[154:157], v[216:219], v[106:109]
	v_mfma_f32_16x16x32_bf16 v[110:113], v[142:145], v[212:215], v[110:113]
	v_mfma_f32_16x16x32_bf16 v[110:113], v[146:149], v[216:219], v[110:113]
	v_mfma_f32_16x16x32_bf16 v[114:117], v[134:137], v[212:215], v[114:117]
	v_mfma_f32_16x16x32_bf16 v[114:117], v[138:141], v[216:219], v[114:117]
	v_mfma_f32_16x16x32_bf16 v[98:101], v[134:137], v[220:223], v[98:101]
	v_mfma_f32_16x16x32_bf16 v[98:101], v[138:141], v[224:227], v[98:101]
	v_mfma_f32_16x16x32_bf16 v[94:97], v[142:145], v[220:223], v[94:97]
	v_mfma_f32_16x16x32_bf16 v[94:97], v[146:149], v[224:227], v[94:97]
	v_mfma_f32_16x16x32_bf16 v[90:93], v[150:153], v[220:223], v[90:93]
	v_mfma_f32_16x16x32_bf16 v[90:93], v[154:157], v[224:227], v[90:93]
	v_mfma_f32_16x16x32_bf16 v[86:89], v[176:179], v[220:223], v[86:89]
	v_mfma_f32_16x16x32_bf16 v[86:89], v[180:183], v[224:227], v[86:89]
	v_mfma_f32_16x16x32_bf16 v[70:73], v[176:179], v[228:231], v[70:73]
	v_mfma_f32_16x16x32_bf16 v[70:73], v[180:183], v[232:235], v[70:73]
	v_mfma_f32_16x16x32_bf16 v[74:77], v[150:153], v[228:231], v[74:77]
	v_mfma_f32_16x16x32_bf16 v[74:77], v[154:157], v[232:235], v[74:77]
	v_mfma_f32_16x16x32_bf16 v[78:81], v[142:145], v[228:231], v[78:81]
	v_mfma_f32_16x16x32_bf16 v[78:81], v[146:149], v[232:235], v[78:81]
	v_mfma_f32_16x16x32_bf16 v[82:85], v[134:137], v[228:231], v[82:85]
	v_mfma_f32_16x16x32_bf16 v[82:85], v[138:141], v[232:235], v[82:85]
	s_barrier
	s_add_i32 s4, s4, s24
	v_lshl_add_u64 v[236:237], s[52:53], 0, v[4:5]
	s_mov_b32 m0, s4
	ds_read_b128 v[184:187], v188 offset:16384
	ds_read_b128 v[190:193], v188 offset:17408
	ds_read_b128 v[212:215], v188 offset:18432
	ds_read_b128 v[216:219], v188 offset:19456
	ds_read_b128 v[220:223], v188 offset:20480
	ds_read_b128 v[224:227], v188 offset:21504
	ds_read_b128 v[228:231], v188 offset:22528
	ds_read_b128 v[232:235], v188 offset:23552
	global_load_lds_dwordx4 v[236:237], off
	s_add_i32 m0, s4, 0x2000
	s_add_u32 s22, s52, 0x160000
	v_lshl_add_u64 v[238:239], s[52:53], 0, v[170:171]
	s_addc_u32 s23, s53, 0
	s_add_i32 s4, s5, s24
	global_load_lds_dwordx4 v[238:239], off
	v_lshl_add_u64 v[240:241], s[22:23], 0, v[4:5]
	s_mov_b32 m0, s4
	v_lshl_add_u64 v[242:243], s[54:55], 0, v[168:169]
	global_load_lds_dwordx4 v[240:241], off
	v_lshl_add_u64 v[240:241], s[22:23], 0, v[170:171]
	s_add_i32 m0, s4, 0x2000
	s_nop 0
	global_load_lds_dwordx4 v[240:241], off
	v_lshl_add_u64 v[240:241], s[54:55], 0, v[2:3]
	s_mov_b32 m0, s56
	s_nop 0
	global_load_lds_dwordx4 v[240:241], off
	s_mov_b32 m0, s57
	s_nop 0
	global_load_lds_dwordx4 v[242:243], off
	s_waitcnt vmcnt(8)
	s_waitcnt lgkmcnt(0)
	s_barrier
; #define PG8_STAGE(bufoff, gbase, voff) do { _Pragma("unroll") for (int _i = 0; _i < 2; ++_i) \
;         __builtin_amdgcn_global_load_lds((const unsigned*)((const char*)(gbase) + (voff)[_i]), (PG8_LAS unsigned*)(lds + (bufoff) + ldsw + _i * 8192), 16, 0, 0); } while (0)
; #define PG8_LDA(dst, b, h) do { _Pragma("unroll") for (int m = 0; m < 4; ++m) _Pragma("unroll") for (int k = 0; k < 2; ++k) dst[m][k] = *(const PG8_LAS bf16x8*)(lds + PG8_SA(b, h) + aoff + m * 2048 + k * 1024); } while (0)
; #define PG8_LDB(dst, b, h) do { _Pragma("unroll") for (int n = 0; n < 2; ++n) _Pragma("unroll") for (int k = 0; k < 2; ++k) dst[n][k] = *(const PG8_LAS bf16x8*)(lds + PG8_SB(b, h) + boff + n * 2048 + k * 1024); } while (0)
; #define PG8_MMA(ai, bj, At, Bt) do { __builtin_amdgcn_s_setprio(1); _Pragma("unroll") for (int m = 0; m < 4; ++m) _Pragma("unroll") for (int n = 0; n < 2; ++n) _Pragma("unroll") for (int k = 0; k < 2; ++k) \
;         acc[ai][bj][m][n] = __builtin_amdgcn_mfma_f32_16x16x32_bf16(Bt[n][k], At[m][k], acc[ai][bj][m][n], 0, 0, 0); __builtin_amdgcn_s_setprio(0); } while (0)
; #define PG8_WAIT_V(n) asm volatile("s_waitcnt vmcnt(" #n ")" ::: "memory")
; #define PG8_WAIT_L(n) asm volatile("s_waitcnt lgkmcnt(" #n ")" ::: "memory")
; #define PG8_BAR __builtin_amdgcn_s_barrier()
; #define PG8_SCHED __builtin_amdgcn_sched_barrier(0)
; template <class Epi, class Sched, bool ALIGN_EPI = false, bool SP2 = false>
; __device__ __forceinline__ void gemm_phase(PG8_LAS unsigned char* lds, const Gemm g, const Sched& S, const Epi& E) {
;     ...
;             PG8_WAIT_V(8); PG8_WAIT_L(0); PG8_BAR; PG8_MMA(1, 0, At, B0); PG8_MMA(1, 1, At, B1); PG8_BAR; PG8_SCHED;
;             PG8_LDB(B0, 1, 0); PG8_LDB(B1, 1, 1); PG8_SCHED; PG8_LDA(At, 1, 0); PG8_STAGE(PG8_SA(0, 1), a2 + hstep, voffA);
;             PG8_WAIT_V(8); PG8_WAIT_L(0); PG8_BAR; PG8_MMA(0, 0, At, B0); PG8_MMA(0, 1, At, B1); PG8_BAR; PG8_SCHED;
	v_mfma_f32_16x16x32_bf16 v[58:61], v[134:137], v[184:187], v[58:61]
	v_mfma_f32_16x16x32_bf16 v[58:61], v[138:141], v[190:193], v[58:61]
	v_mfma_f32_16x16x32_bf16 v[54:57], v[142:145], v[184:187], v[54:57]
	v_mfma_f32_16x16x32_bf16 v[54:57], v[146:149], v[190:193], v[54:57]
	v_mfma_f32_16x16x32_bf16 v[66:69], v[150:153], v[184:187], v[66:69]
	v_mfma_f32_16x16x32_bf16 v[66:69], v[154:157], v[190:193], v[66:69]
	v_mfma_f32_16x16x32_bf16 v[62:65], v[176:179], v[184:187], v[62:65]
	v_mfma_f32_16x16x32_bf16 v[62:65], v[180:183], v[190:193], v[62:65]
	v_mfma_f32_16x16x32_bf16 v[38:41], v[176:179], v[212:215], v[38:41]
	v_mfma_f32_16x16x32_bf16 v[38:41], v[180:183], v[216:219], v[38:41]
	v_mfma_f32_16x16x32_bf16 v[42:45], v[150:153], v[212:215], v[42:45]
	v_mfma_f32_16x16x32_bf16 v[42:45], v[154:157], v[216:219], v[42:45]
	v_mfma_f32_16x16x32_bf16 v[46:49], v[142:145], v[212:215], v[46:49]
	v_mfma_f32_16x16x32_bf16 v[46:49], v[146:149], v[216:219], v[46:49]
	v_mfma_f32_16x16x32_bf16 v[50:53], v[134:137], v[212:215], v[50:53]
	v_mfma_f32_16x16x32_bf16 v[50:53], v[138:141], v[216:219], v[50:53]
	v_mfma_f32_16x16x32_bf16 v[34:37], v[134:137], v[220:223], v[34:37]
	v_mfma_f32_16x16x32_bf16 v[34:37], v[138:141], v[224:227], v[34:37]
	v_mfma_f32_16x16x32_bf16 v[30:33], v[142:145], v[220:223], v[30:33]
	v_mfma_f32_16x16x32_bf16 v[30:33], v[146:149], v[224:227], v[30:33]
	v_mfma_f32_16x16x32_bf16 v[26:29], v[150:153], v[220:223], v[26:29]
	v_mfma_f32_16x16x32_bf16 v[26:29], v[154:157], v[224:227], v[26:29]
	v_mfma_f32_16x16x32_bf16 v[22:25], v[176:179], v[220:223], v[22:25]
	v_mfma_f32_16x16x32_bf16 v[22:25], v[180:183], v[224:227], v[22:25]
	v_mfma_f32_16x16x32_bf16 v[6:9], v[176:179], v[228:231], v[6:9]
	v_mfma_f32_16x16x32_bf16 v[6:9], v[180:183], v[232:235], v[6:9]
	v_mfma_f32_16x16x32_bf16 v[10:13], v[150:153], v[228:231], v[10:13]
	v_mfma_f32_16x16x32_bf16 v[10:13], v[154:157], v[232:235], v[10:13]
	v_mfma_f32_16x16x32_bf16 v[14:17], v[142:145], v[228:231], v[14:17]
	v_mfma_f32_16x16x32_bf16 v[14:17], v[146:149], v[232:235], v[14:17]
	v_mfma_f32_16x16x32_bf16 v[18:21], v[134:137], v[228:231], v[18:21]
	v_mfma_f32_16x16x32_bf16 v[18:21], v[138:141], v[232:235], v[18:21]
	s_barrier
	s_add_i32 s4, 0, 0x18000
	s_add_i32 s5, 0, 0x1c000
	v_add_u32_e32 v146, s4, v158
	v_add_u32_e32 v180, s5, v158
	ds_read_b128 v[134:137], v146
	ds_read_b128 v[138:141], v146 offset:1024
	ds_read_b128 v[142:145], v146 offset:2048
	ds_read_b128 v[146:149], v146 offset:3072
	ds_read_b128 v[150:153], v180
	ds_read_b128 v[154:157], v180 offset:1024
	ds_read_b128 v[176:179], v180 offset:2048
	ds_read_b128 v[180:183], v180 offset:3072
	s_add_u32 s22, s54, 0x160000
	s_addc_u32 s23, s55, 0
	s_mov_b32 m0, s59
	v_lshl_add_u64 v[244:245], s[22:23], 0, v[2:3]
	ds_read_b128 v[184:187], v188 offset:32768
	ds_read_b128 v[190:193], v188 offset:33792
	ds_read_b128 v[212:215], v188 offset:34816
	ds_read_b128 v[216:219], v188 offset:35840
	ds_read_b128 v[220:223], v188 offset:36864
	ds_read_b128 v[224:227], v188 offset:37888
	ds_read_b128 v[228:231], v188 offset:38912
	ds_read_b128 v[232:235], v188 offset:39936
	global_load_lds_dwordx4 v[244:245], off
	v_lshl_add_u64 v[244:245], s[22:23], 0, v[168:169]
	s_mov_b32 m0, s60
	s_nop 0
	global_load_lds_dwordx4 v[244:245], off
	s_waitcnt vmcnt(8)
	s_waitcnt lgkmcnt(0)
	s_barrier
	v_mfma_f32_16x16x32_bf16 v[122:125], v[134:137], v[184:187], v[122:125]
	v_mfma_f32_16x16x32_bf16 v[122:125], v[138:141], v[190:193], v[122:125]
	v_mfma_f32_16x16x32_bf16 v[118:121], v[142:145], v[184:187], v[118:121]
	v_mfma_f32_16x16x32_bf16 v[118:121], v[146:149], v[190:193], v[118:121]
	v_mfma_f32_16x16x32_bf16 v[130:133], v[150:153], v[184:187], v[130:133]
	v_mfma_f32_16x16x32_bf16 v[130:133], v[154:157], v[190:193], v[130:133]
	v_mfma_f32_16x16x32_bf16 v[126:129], v[176:179], v[184:187], v[126:129]
	v_mfma_f32_16x16x32_bf16 v[126:129], v[180:183], v[190:193], v[126:129]
	v_mfma_f32_16x16x32_bf16 v[102:105], v[176:179], v[212:215], v[102:105]
	v_mfma_f32_16x16x32_bf16 v[102:105], v[180:183], v[216:219], v[102:105]
	v_mfma_f32_16x16x32_bf16 v[106:109], v[150:153], v[212:215], v[106:109]
	v_mfma_f32_16x16x32_bf16 v[106:109], v[154:157], v[216:219], v[106:109]
	v_mfma_f32_16x16x32_bf16 v[110:113], v[142:145], v[212:215], v[110:113]
	v_mfma_f32_16x16x32_bf16 v[110:113], v[146:149], v[216:219], v[110:113]
	v_mfma_f32_16x16x32_bf16 v[114:117], v[134:137], v[212:215], v[114:117]
	v_mfma_f32_16x16x32_bf16 v[114:117], v[138:141], v[216:219], v[114:117]
	v_mfma_f32_16x16x32_bf16 v[98:101], v[134:137], v[220:223], v[98:101]
	v_mfma_f32_16x16x32_bf16 v[98:101], v[138:141], v[224:227], v[98:101]
	v_mfma_f32_16x16x32_bf16 v[94:97], v[142:145], v[220:223], v[94:97]
	v_mfma_f32_16x16x32_bf16 v[94:97], v[146:149], v[224:227], v[94:97]
	v_mfma_f32_16x16x32_bf16 v[90:93], v[150:153], v[220:223], v[90:93]
	v_mfma_f32_16x16x32_bf16 v[90:93], v[154:157], v[224:227], v[90:93]
	v_mfma_f32_16x16x32_bf16 v[86:89], v[176:179], v[220:223], v[86:89]
	v_mfma_f32_16x16x32_bf16 v[86:89], v[180:183], v[224:227], v[86:89]
	v_mfma_f32_16x16x32_bf16 v[70:73], v[176:179], v[228:231], v[70:73]
	v_mfma_f32_16x16x32_bf16 v[70:73], v[180:183], v[232:235], v[70:73]
	v_mfma_f32_16x16x32_bf16 v[74:77], v[150:153], v[228:231], v[74:77]
	v_mfma_f32_16x16x32_bf16 v[74:77], v[154:157], v[232:235], v[74:77]
	v_mfma_f32_16x16x32_bf16 v[78:81], v[142:145], v[228:231], v[78:81]
	v_mfma_f32_16x16x32_bf16 v[78:81], v[146:149], v[232:235], v[78:81]
	v_mfma_f32_16x16x32_bf16 v[82:85], v[134:137], v[228:231], v[82:85]
	v_mfma_f32_16x16x32_bf16 v[82:85], v[138:141], v[232:235], v[82:85]
	s_barrier
; #define PG8_STAGE(bufoff, gbase, voff) do { _Pragma("unroll") for (int _i = 0; _i < 2; ++_i) \
;         __builtin_amdgcn_global_load_lds((const unsigned*)((const char*)(gbase) + (voff)[_i]), (PG8_LAS unsigned*)(lds + (bufoff) + ldsw + _i * 8192), 16, 0, 0); } while (0)
; #define PG8_LDA(dst, b, h) do { _Pragma("unroll") for (int m = 0; m < 4; ++m) _Pragma("unroll") for (int k = 0; k < 2; ++k) dst[m][k] = *(const PG8_LAS bf16x8*)(lds + PG8_SA(b, h) + aoff + m * 2048 + k * 1024); } while (0)
; #define PG8_MMA(ai, bj, At, Bt) do { __builtin_amdgcn_s_setprio(1); _Pragma("unroll") for (int m = 0; m < 4; ++m) _Pragma("unroll") for (int n = 0; n < 2; ++n) _Pragma("unroll") for (int k = 0; k < 2; ++k) \
;         acc[ai][bj][m][n] = __builtin_amdgcn_mfma_f32_16x16x32_bf16(Bt[n][k], At[m][k], acc[ai][bj][m][n], 0, 0, 0); __builtin_amdgcn_s_setprio(0); } while (0)
; #define PG8_WAIT_V(n) asm volatile("s_waitcnt vmcnt(" #n ")" ::: "memory")
; #define PG8_WAIT_L(n) asm volatile("s_waitcnt lgkmcnt(" #n ")" ::: "memory")
; #define PG8_BAR __builtin_amdgcn_s_barrier()
; #define PG8_SCHED __builtin_amdgcn_sched_barrier(0)
; template <class Epi, class Sched, bool ALIGN_EPI = false, bool SP2 = false>
; __device__ __forceinline__ void gemm_phase(PG8_LAS unsigned char* lds, const Gemm g, const Sched& S, const Epi& E) {
;     ...
;         for (int t = 0; t < nt; t += 2) {
;     ...
;             PG8_LDA(At, 1, 1); PG8_STAGE(PG8_SB(1, 0), b3, voffB); PG8_STAGE(PG8_SB(1, 1), b3 + hstep, voffB); PG8_STAGE(PG8_SA(1, 0), a3, voffA);
;             PG8_WAIT_V(8); PG8_WAIT_L(0); PG8_BAR; PG8_MMA(1, 0, At, B0); PG8_MMA(1, 1, At, B1); PG8_BAR; PG8_SCHED;
	s_add_i32 s4, s4, s24
	v_lshl_add_u64 v[236:237], v[236:237], 0, s[28:29]
	s_mov_b32 m0, s4
	ds_read_b128 v[184:187], v188 offset:49152
	ds_read_b128 v[190:193], v188 offset:50176
	ds_read_b128 v[212:215], v188 offset:51200
	ds_read_b128 v[216:219], v188 offset:52224
	ds_read_b128 v[220:223], v188 offset:53248
	ds_read_b128 v[224:227], v188 offset:54272
	ds_read_b128 v[228:231], v188 offset:55296
	ds_read_b128 v[232:235], v188 offset:56320
	global_load_lds_dwordx4 v[236:237], off
	s_add_i32 m0, s4, 0x2000
	s_add_u32 s22, s52, 0x160080
	v_lshl_add_u64 v[236:237], v[238:239], 0, s[28:29]
	s_addc_u32 s23, s53, 0
	s_add_i32 s4, s5, s24
	global_load_lds_dwordx4 v[236:237], off
	v_lshl_add_u64 v[236:237], s[22:23], 0, v[4:5]
	s_mov_b32 m0, s4
	s_nop 0
	global_load_lds_dwordx4 v[236:237], off
	v_lshl_add_u64 v[236:237], s[22:23], 0, v[170:171]
	s_add_i32 m0, s4, 0x2000
	s_nop 0
	global_load_lds_dwordx4 v[236:237], off
	v_lshl_add_u64 v[236:237], v[240:241], 0, s[28:29]
	s_mov_b32 m0, s61
	s_nop 0
	global_load_lds_dwordx4 v[236:237], off
	v_lshl_add_u64 v[236:237], v[242:243], 0, s[28:29]
	s_mov_b32 m0, s64
	s_nop 0
	global_load_lds_dwordx4 v[236:237], off
	s_waitcnt vmcnt(8)
	s_waitcnt lgkmcnt(0)
	s_barrier
	v_mfma_f32_16x16x32_bf16 v[58:61], v[134:137], v[184:187], v[58:61]
	v_mfma_f32_16x16x32_bf16 v[58:61], v[138:141], v[190:193], v[58:61]
	v_mfma_f32_16x16x32_bf16 v[54:57], v[142:145], v[184:187], v[54:57]
	v_mfma_f32_16x16x32_bf16 v[54:57], v[146:149], v[190:193], v[54:57]
	v_mfma_f32_16x16x32_bf16 v[66:69], v[150:153], v[184:187], v[66:69]
	v_mfma_f32_16x16x32_bf16 v[66:69], v[154:157], v[190:193], v[66:69]
	v_mfma_f32_16x16x32_bf16 v[62:65], v[176:179], v[184:187], v[62:65]
	v_mfma_f32_16x16x32_bf16 v[62:65], v[180:183], v[190:193], v[62:65]
	v_mfma_f32_16x16x32_bf16 v[38:41], v[176:179], v[212:215], v[38:41]
	v_mfma_f32_16x16x32_bf16 v[38:41], v[180:183], v[216:219], v[38:41]
	v_mfma_f32_16x16x32_bf16 v[42:45], v[150:153], v[212:215], v[42:45]
	v_mfma_f32_16x16x32_bf16 v[42:45], v[154:157], v[216:219], v[42:45]
	v_mfma_f32_16x16x32_bf16 v[46:49], v[142:145], v[212:215], v[46:49]
	v_mfma_f32_16x16x32_bf16 v[46:49], v[146:149], v[216:219], v[46:49]
	v_mfma_f32_16x16x32_bf16 v[50:53], v[134:137], v[212:215], v[50:53]
	v_mfma_f32_16x16x32_bf16 v[50:53], v[138:141], v[216:219], v[50:53]
	v_mfma_f32_16x16x32_bf16 v[34:37], v[134:137], v[220:223], v[34:37]
	v_mfma_f32_16x16x32_bf16 v[34:37], v[138:141], v[224:227], v[34:37]
	v_mfma_f32_16x16x32_bf16 v[30:33], v[142:145], v[220:223], v[30:33]
	v_mfma_f32_16x16x32_bf16 v[30:33], v[146:149], v[224:227], v[30:33]
	v_mfma_f32_16x16x32_bf16 v[26:29], v[150:153], v[220:223], v[26:29]
	v_mfma_f32_16x16x32_bf16 v[26:29], v[154:157], v[224:227], v[26:29]
	v_mfma_f32_16x16x32_bf16 v[22:25], v[176:179], v[220:223], v[22:25]
	v_mfma_f32_16x16x32_bf16 v[22:25], v[180:183], v[224:227], v[22:25]
	v_mfma_f32_16x16x32_bf16 v[6:9], v[176:179], v[228:231], v[6:9]
	v_mfma_f32_16x16x32_bf16 v[6:9], v[180:183], v[232:235], v[6:9]
	v_mfma_f32_16x16x32_bf16 v[10:13], v[150:153], v[228:231], v[10:13]
	v_mfma_f32_16x16x32_bf16 v[10:13], v[154:157], v[232:235], v[10:13]
	v_mfma_f32_16x16x32_bf16 v[14:17], v[142:145], v[228:231], v[14:17]
	v_mfma_f32_16x16x32_bf16 v[14:17], v[146:149], v[232:235], v[14:17]
	v_mfma_f32_16x16x32_bf16 v[18:21], v[134:137], v[228:231], v[18:21]
	v_mfma_f32_16x16x32_bf16 v[18:21], v[138:141], v[232:235], v[18:21]
	s_barrier
	s_add_i32 s20, s20, 2
	s_add_u32 s33, s33, 0x100
	s_addc_u32 s69, s69, 0
	s_cmpk_gt_u32 s20, 0x55
	s_mov_b64 s[22:23], s[50:51]
	s_cbranch_scc0 .LBB0_299
	s_and_b64 vcc, exec, s[46:47]
	s_cbranch_vccz .LBB0_302
	s_barrier

; #define PG8_STAGE(bufoff, gbase, voff) do { _Pragma("unroll") for (int _i = 0; _i < 2; ++_i) \
;         __builtin_amdgcn_global_load_lds((const unsigned*)((const char*)(gbase) + (voff)[_i]), (PG8_LAS unsigned*)(lds + (bufoff) + ldsw + _i * 8192), 16, 0, 0); } while (0)
; #define PG8_LDA(dst, b, h) do { _Pragma("unroll") for (int m = 0; m < 4; ++m) _Pragma("unroll") for (int k = 0; k < 2; ++k) dst[m][k] = *(const PG8_LAS bf16x8*)(lds + PG8_SA(b, h) + aoff + m * 2048 + k * 1024); } while (0)
; #define PG8_LDB(dst, b, h) do { _Pragma("unroll") for (int n = 0; n < 2; ++n) _Pragma("unroll") for (int k = 0; k < 2; ++k) dst[n][k] = *(const PG8_LAS bf16x8*)(lds + PG8_SB(b, h) + boff + n * 2048 + k * 1024); } while (0)
; #define PG8_MMA(ai, bj, At, Bt) do { __builtin_amdgcn_s_setprio(1); _Pragma("unroll") for (int m = 0; m < 4; ++m) _Pragma("unroll") for (int n = 0; n < 2; ++n) _Pragma("unroll") for (int k = 0; k < 2; ++k) \
;         acc[ai][bj][m][n] = __builtin_amdgcn_mfma_f32_16x16x32_bf16(Bt[n][k], At[m][k], acc[ai][bj][m][n], 0, 0, 0); __builtin_amdgcn_s_setprio(0); } while (0)
; #define PG8_WAIT_V(n) asm volatile("s_waitcnt vmcnt(" #n ")" ::: "memory")
; #define PG8_WAIT_L(n) asm volatile("s_waitcnt lgkmcnt(" #n ")" ::: "memory")
; #define PG8_BAR __builtin_amdgcn_s_barrier()
; #define PG8_SCHED __builtin_amdgcn_sched_barrier(0)
; template <class Epi, class Sched, bool ALIGN_EPI = false, bool SP2 = false>
; __device__ __forceinline__ void gemm_phase(PG8_LAS unsigned char* lds, const Gemm g, const Sched& S, const Epi& E) {
;     ...
;             const bool last = (t == nt - 2);
;             const char* a1 = cA + (size_t)(t + 1) * kstep;
;             const char* a2 = last ? nA : cA + (size_t)(t + 2) * kstep; const char* b2 = last ? nB : cB + (size_t)(t + 2) * kstep;
;             const char* a3 = a2 + kstep; const char* b3 = b2 + kstep;
;             if (last && has_next) S.a_ready(nxt);
;             if constexpr (SP2) {
;             PG8_LDB(B0, 0, 0); PG8_LDB(B1, 0, 1); PG8_SCHED; PG8_LDA(At, 0, 0); PG8_STAGE(PG8_SA(1, 1), a1 + hstep, voffA);
;             PG8_WAIT_V(8); PG8_WAIT_L(0); PG8_BAR; PG8_MMA(0, 0, At, B0); PG8_MMA(0, 1, At, B1); PG8_BAR; PG8_SCHED;
;             PG8_LDA(At, 0, 1); PG8_STAGE(PG8_SB(0, 0), b2, voffB); PG8_STAGE(PG8_SB(0, 1), b2 + hstep, voffB); PG8_STAGE(PG8_SA(0, 0), a2, voffA);
.LBB0_387:
	s_add_u32 s4, s56, 0xfff80080
	s_addc_u32 s5, s57, -1
	s_add_i32 s6, 0, 0x10000
	s_cmp_eq_u32 s20, 28
	s_cselect_b32 s59, s47, s5
	s_cselect_b32 s58, s75, s4
	v_add_u32_e32 v156, s6, v153
	s_cselect_b32 s55, s49, s77
	s_cselect_b32 s54, vcc_lo, s71
	s_add_i32 s4, 0, 0x14000
	ds_read_b128 v[144:147], v156
	ds_read_b128 v[148:151], v156 offset:1024
	ds_read_b128 v[168:171], v156 offset:2048
	ds_read_b128 v[172:175], v156 offset:3072
	v_add_u32_e32 v156, s4, v153
	ds_read_b128 v[176:179], v156
	ds_read_b128 v[180:183], v156 offset:1024
	ds_read_b128 v[184:187], v156 offset:2048
	ds_read_b128 v[188:191], v156 offset:3072
	v_lshl_add_u64 v[156:157], s[56:57], 0, v[140:141]
	s_add_i32 m0, s60, 0xc000
	ds_read_b128 v[212:215], v155
	ds_read_b128 v[216:219], v155 offset:1024
	ds_read_b128 v[220:223], v155 offset:2048
	ds_read_b128 v[224:227], v155 offset:3072
	ds_read_b128 v[228:231], v155 offset:4096
	ds_read_b128 v[232:235], v155 offset:5120
	ds_read_b128 v[236:239], v155 offset:6144
	ds_read_b128 v[240:243], v155 offset:7168
	global_load_lds_dwordx4 v[156:157], off
	v_lshl_add_u64 v[156:157], s[56:57], 0, v[142:143]
	s_add_i32 m0, s60, 0xe000
	s_nop 0
	global_load_lds_dwordx4 v[156:157], off
	s_waitcnt vmcnt(8)
	s_waitcnt lgkmcnt(0)
	s_barrier
	v_mfma_f32_16x16x32_bf16 v[122:125], v[144:147], v[212:215], v[122:125]
	v_mfma_f32_16x16x32_bf16 v[122:125], v[148:151], v[216:219], v[122:125]
	v_mfma_f32_16x16x32_bf16 v[118:121], v[168:171], v[212:215], v[118:121]
	v_mfma_f32_16x16x32_bf16 v[118:121], v[172:175], v[216:219], v[118:121]
	v_mfma_f32_16x16x32_bf16 v[130:133], v[176:179], v[212:215], v[130:133]
	v_mfma_f32_16x16x32_bf16 v[130:133], v[180:183], v[216:219], v[130:133]
	v_mfma_f32_16x16x32_bf16 v[126:129], v[184:187], v[212:215], v[126:129]
	v_mfma_f32_16x16x32_bf16 v[126:129], v[188:191], v[216:219], v[126:129]
	v_mfma_f32_16x16x32_bf16 v[110:113], v[184:187], v[220:223], v[110:113]
	v_mfma_f32_16x16x32_bf16 v[110:113], v[188:191], v[224:227], v[110:113]
	v_mfma_f32_16x16x32_bf16 v[114:117], v[176:179], v[220:223], v[114:117]
	v_mfma_f32_16x16x32_bf16 v[114:117], v[180:183], v[224:227], v[114:117]
	v_mfma_f32_16x16x32_bf16 v[102:105], v[168:171], v[220:223], v[102:105]
	v_mfma_f32_16x16x32_bf16 v[102:105], v[172:175], v[224:227], v[102:105]
	v_mfma_f32_16x16x32_bf16 v[106:109], v[144:147], v[220:223], v[106:109]
	v_mfma_f32_16x16x32_bf16 v[106:109], v[148:151], v[224:227], v[106:109]
	v_mfma_f32_16x16x32_bf16 v[90:93], v[144:147], v[228:231], v[90:93]
	v_mfma_f32_16x16x32_bf16 v[90:93], v[148:151], v[232:235], v[90:93]
	v_mfma_f32_16x16x32_bf16 v[86:89], v[168:171], v[228:231], v[86:89]
	v_mfma_f32_16x16x32_bf16 v[86:89], v[172:175], v[232:235], v[86:89]
	v_mfma_f32_16x16x32_bf16 v[98:101], v[176:179], v[228:231], v[98:101]
	v_mfma_f32_16x16x32_bf16 v[98:101], v[180:183], v[232:235], v[98:101]
	v_mfma_f32_16x16x32_bf16 v[94:97], v[184:187], v[228:231], v[94:97]
	v_mfma_f32_16x16x32_bf16 v[94:97], v[188:191], v[232:235], v[94:97]
	v_mfma_f32_16x16x32_bf16 v[78:81], v[184:187], v[236:239], v[78:81]
	v_mfma_f32_16x16x32_bf16 v[78:81], v[188:191], v[240:243], v[78:81]
	v_mfma_f32_16x16x32_bf16 v[82:85], v[176:179], v[236:239], v[82:85]
	v_mfma_f32_16x16x32_bf16 v[82:85], v[180:183], v[240:243], v[82:85]
	v_mfma_f32_16x16x32_bf16 v[70:73], v[168:171], v[236:239], v[70:73]
	v_mfma_f32_16x16x32_bf16 v[70:73], v[172:175], v[240:243], v[70:73]
	v_mfma_f32_16x16x32_bf16 v[74:77], v[144:147], v[236:239], v[74:77]
	v_mfma_f32_16x16x32_bf16 v[74:77], v[148:151], v[240:243], v[74:77]
	s_barrier
	s_add_i32 s5, s6, s24
	v_lshl_add_u64 v[156:157], s[54:55], 0, v[4:5]
	s_mov_b32 m0, s5
	ds_read_b128 v[212:215], v155 offset:16384
	ds_read_b128 v[216:219], v155 offset:17408
	ds_read_b128 v[220:223], v155 offset:18432
	ds_read_b128 v[224:227], v155 offset:19456
	ds_read_b128 v[228:231], v155 offset:20480
	ds_read_b128 v[232:235], v155 offset:21504
	ds_read_b128 v[236:239], v155 offset:22528
	ds_read_b128 v[240:243], v155 offset:23552
	global_load_lds_dwordx4 v[156:157], off
	s_add_i32 m0, s5, 0x2000
	s_add_u32 s34, s54, 0x80000
	v_lshl_add_u64 v[192:193], s[54:55], 0, v[2:3]
	s_addc_u32 s35, s55, 0
	s_add_i32 s4, s4, s24
	global_load_lds_dwordx4 v[192:193], off
	v_lshl_add_u64 v[244:245], s[34:35], 0, v[4:5]
	s_mov_b32 m0, s4
	v_lshl_add_u64 v[246:247], s[58:59], 0, v[134:135]
	global_load_lds_dwordx4 v[244:245], off
	v_lshl_add_u64 v[244:245], s[34:35], 0, v[2:3]
	s_add_i32 m0, s4, 0x2000
	s_nop 0
	global_load_lds_dwordx4 v[244:245], off
	v_lshl_add_u64 v[244:245], s[58:59], 0, v[136:137]
	s_mov_b32 m0, s60
	s_nop 0
	global_load_lds_dwordx4 v[244:245], off
	s_mov_b32 m0, s61
	s_nop 0
	global_load_lds_dwordx4 v[246:247], off
	s_waitcnt vmcnt(8)
	s_waitcnt lgkmcnt(0)
	s_barrier
; #define PG8_STAGE(bufoff, gbase, voff) do { _Pragma("unroll") for (int _i = 0; _i < 2; ++_i) \
;         __builtin_amdgcn_global_load_lds((const unsigned*)((const char*)(gbase) + (voff)[_i]), (PG8_LAS unsigned*)(lds + (bufoff) + ldsw + _i * 8192), 16, 0, 0); } while (0)
; #define PG8_LDA(dst, b, h) do { _Pragma("unroll") for (int m = 0; m < 4; ++m) _Pragma("unroll") for (int k = 0; k < 2; ++k) dst[m][k] = *(const PG8_LAS bf16x8*)(lds + PG8_SA(b, h) + aoff + m * 2048 + k * 1024); } while (0)
; #define PG8_LDB(dst, b, h) do { _Pragma("unroll") for (int n = 0; n < 2; ++n) _Pragma("unroll") for (int k = 0; k < 2; ++k) dst[n][k] = *(const PG8_LAS bf16x8*)(lds + PG8_SB(b, h) + boff + n * 2048 + k * 1024); } while (0)
; #define PG8_MMA(ai, bj, At, Bt) do { __builtin_amdgcn_s_setprio(1); _Pragma("unroll") for (int m = 0; m < 4; ++m) _Pragma("unroll") for (int n = 0; n < 2; ++n) _Pragma("unroll") for (int k = 0; k < 2; ++k) \
;         acc[ai][bj][m][n] = __builtin_amdgcn_mfma_f32_16x16x32_bf16(Bt[n][k], At[m][k], acc[ai][bj][m][n], 0, 0, 0); __builtin_amdgcn_s_setprio(0); } while (0)
; #define PG8_WAIT_V(n) asm volatile("s_waitcnt vmcnt(" #n ")" ::: "memory")
; #define PG8_WAIT_L(n) asm volatile("s_waitcnt lgkmcnt(" #n ")" ::: "memory")
; #define PG8_BAR __builtin_amdgcn_s_barrier()
; #define PG8_SCHED __builtin_amdgcn_sched_barrier(0)
; template <class Epi, class Sched, bool ALIGN_EPI = false, bool SP2 = false>
; __device__ __forceinline__ void gemm_phase(PG8_LAS unsigned char* lds, const Gemm g, const Sched& S, const Epi& E) {
;     ...
;             PG8_WAIT_V(8); PG8_WAIT_L(0); PG8_BAR; PG8_MMA(1, 0, At, B0); PG8_MMA(1, 1, At, B1); PG8_BAR; PG8_SCHED;
;             PG8_LDB(B0, 1, 0); PG8_LDB(B1, 1, 1); PG8_SCHED; PG8_LDA(At, 1, 0); PG8_STAGE(PG8_SA(0, 1), a2 + hstep, voffA);
;             PG8_WAIT_V(8); PG8_WAIT_L(0); PG8_BAR; PG8_MMA(0, 0, At, B0); PG8_MMA(0, 1, At, B1); PG8_BAR; PG8_SCHED;
	v_mfma_f32_16x16x32_bf16 v[58:61], v[144:147], v[212:215], v[58:61]
	v_mfma_f32_16x16x32_bf16 v[58:61], v[148:151], v[216:219], v[58:61]
	v_mfma_f32_16x16x32_bf16 v[54:57], v[168:171], v[212:215], v[54:57]
	v_mfma_f32_16x16x32_bf16 v[54:57], v[172:175], v[216:219], v[54:57]
	v_mfma_f32_16x16x32_bf16 v[66:69], v[176:179], v[212:215], v[66:69]
	v_mfma_f32_16x16x32_bf16 v[66:69], v[180:183], v[216:219], v[66:69]
	v_mfma_f32_16x16x32_bf16 v[62:65], v[184:187], v[212:215], v[62:65]
	v_mfma_f32_16x16x32_bf16 v[62:65], v[188:191], v[216:219], v[62:65]
	v_mfma_f32_16x16x32_bf16 v[46:49], v[184:187], v[220:223], v[46:49]
	v_mfma_f32_16x16x32_bf16 v[46:49], v[188:191], v[224:227], v[46:49]
	v_mfma_f32_16x16x32_bf16 v[50:53], v[176:179], v[220:223], v[50:53]
	v_mfma_f32_16x16x32_bf16 v[50:53], v[180:183], v[224:227], v[50:53]
	v_mfma_f32_16x16x32_bf16 v[38:41], v[168:171], v[220:223], v[38:41]
	v_mfma_f32_16x16x32_bf16 v[38:41], v[172:175], v[224:227], v[38:41]
	v_mfma_f32_16x16x32_bf16 v[42:45], v[144:147], v[220:223], v[42:45]
	v_mfma_f32_16x16x32_bf16 v[42:45], v[148:151], v[224:227], v[42:45]
	v_mfma_f32_16x16x32_bf16 v[26:29], v[144:147], v[228:231], v[26:29]
	v_mfma_f32_16x16x32_bf16 v[26:29], v[148:151], v[232:235], v[26:29]
	v_mfma_f32_16x16x32_bf16 v[22:25], v[168:171], v[228:231], v[22:25]
	v_mfma_f32_16x16x32_bf16 v[22:25], v[172:175], v[232:235], v[22:25]
	v_mfma_f32_16x16x32_bf16 v[34:37], v[176:179], v[228:231], v[34:37]
	v_mfma_f32_16x16x32_bf16 v[34:37], v[180:183], v[232:235], v[34:37]
	v_mfma_f32_16x16x32_bf16 v[30:33], v[184:187], v[228:231], v[30:33]
	v_mfma_f32_16x16x32_bf16 v[30:33], v[188:191], v[232:235], v[30:33]
	v_mfma_f32_16x16x32_bf16 v[18:21], v[184:187], v[236:239], v[18:21]
	v_mfma_f32_16x16x32_bf16 v[18:21], v[188:191], v[240:243], v[18:21]
	v_mfma_f32_16x16x32_bf16 v[14:17], v[176:179], v[236:239], v[14:17]
	v_mfma_f32_16x16x32_bf16 v[14:17], v[180:183], v[240:243], v[14:17]
	v_mfma_f32_16x16x32_bf16 v[6:9], v[168:171], v[236:239], v[6:9]
	v_mfma_f32_16x16x32_bf16 v[6:9], v[172:175], v[240:243], v[6:9]
	v_mfma_f32_16x16x32_bf16 v[10:13], v[144:147], v[236:239], v[10:13]
	v_mfma_f32_16x16x32_bf16 v[10:13], v[148:151], v[240:243], v[10:13]
	s_barrier
	s_add_i32 s4, 0, 0x18000
	v_add_u32_e32 v158, s4, v153
	s_add_i32 s5, 0, 0x1c000
	ds_read_b128 v[144:147], v158
	ds_read_b128 v[148:151], v158 offset:1024
	ds_read_b128 v[168:171], v158 offset:2048
	ds_read_b128 v[172:175], v158 offset:3072
	v_add_u32_e32 v158, s5, v153
	ds_read_b128 v[176:179], v158
	ds_read_b128 v[180:183], v158 offset:1024
	ds_read_b128 v[184:187], v158 offset:2048
	ds_read_b128 v[188:191], v158 offset:3072
	s_add_u32 s34, s58, 0x80000
	s_addc_u32 s35, s59, 0
	s_mov_b32 m0, s64
	v_lshl_add_u64 v[248:249], s[34:35], 0, v[136:137]
	ds_read_b128 v[212:215], v155 offset:32768
	ds_read_b128 v[216:219], v155 offset:33792
	ds_read_b128 v[220:223], v155 offset:34816
	ds_read_b128 v[224:227], v155 offset:35840
	ds_read_b128 v[228:231], v155 offset:36864
	ds_read_b128 v[232:235], v155 offset:37888
	ds_read_b128 v[236:239], v155 offset:38912
	ds_read_b128 v[240:243], v155 offset:39936
	global_load_lds_dwordx4 v[248:249], off
	v_lshl_add_u64 v[248:249], s[34:35], 0, v[134:135]
	s_mov_b32 m0, s65
	s_nop 0
	global_load_lds_dwordx4 v[248:249], off
	s_waitcnt vmcnt(8)
	s_waitcnt lgkmcnt(0)
	s_barrier
	v_mfma_f32_16x16x32_bf16 v[122:125], v[144:147], v[212:215], v[122:125]
	v_mfma_f32_16x16x32_bf16 v[122:125], v[148:151], v[216:219], v[122:125]
	v_mfma_f32_16x16x32_bf16 v[118:121], v[168:171], v[212:215], v[118:121]
	v_mfma_f32_16x16x32_bf16 v[118:121], v[172:175], v[216:219], v[118:121]
	v_mfma_f32_16x16x32_bf16 v[130:133], v[176:179], v[212:215], v[130:133]
	v_mfma_f32_16x16x32_bf16 v[130:133], v[180:183], v[216:219], v[130:133]
	v_mfma_f32_16x16x32_bf16 v[126:129], v[184:187], v[212:215], v[126:129]
	v_mfma_f32_16x16x32_bf16 v[126:129], v[188:191], v[216:219], v[126:129]
	v_mfma_f32_16x16x32_bf16 v[110:113], v[184:187], v[220:223], v[110:113]
	v_mfma_f32_16x16x32_bf16 v[110:113], v[188:191], v[224:227], v[110:113]
	v_mfma_f32_16x16x32_bf16 v[114:117], v[176:179], v[220:223], v[114:117]
	v_mfma_f32_16x16x32_bf16 v[114:117], v[180:183], v[224:227], v[114:117]
	v_mfma_f32_16x16x32_bf16 v[102:105], v[168:171], v[220:223], v[102:105]
	v_mfma_f32_16x16x32_bf16 v[102:105], v[172:175], v[224:227], v[102:105]
	v_mfma_f32_16x16x32_bf16 v[106:109], v[144:147], v[220:223], v[106:109]
	v_mfma_f32_16x16x32_bf16 v[106:109], v[148:151], v[224:227], v[106:109]
	v_mfma_f32_16x16x32_bf16 v[90:93], v[144:147], v[228:231], v[90:93]
	v_mfma_f32_16x16x32_bf16 v[90:93], v[148:151], v[232:235], v[90:93]
	v_mfma_f32_16x16x32_bf16 v[86:89], v[168:171], v[228:231], v[86:89]
	v_mfma_f32_16x16x32_bf16 v[86:89], v[172:175], v[232:235], v[86:89]
	v_mfma_f32_16x16x32_bf16 v[98:101], v[176:179], v[228:231], v[98:101]
	v_mfma_f32_16x16x32_bf16 v[98:101], v[180:183], v[232:235], v[98:101]
	v_mfma_f32_16x16x32_bf16 v[94:97], v[184:187], v[228:231], v[94:97]
	v_mfma_f32_16x16x32_bf16 v[94:97], v[188:191], v[232:235], v[94:97]
	v_mfma_f32_16x16x32_bf16 v[78:81], v[184:187], v[236:239], v[78:81]
	v_mfma_f32_16x16x32_bf16 v[78:81], v[188:191], v[240:243], v[78:81]
	v_mfma_f32_16x16x32_bf16 v[82:85], v[176:179], v[236:239], v[82:85]
	v_mfma_f32_16x16x32_bf16 v[82:85], v[180:183], v[240:243], v[82:85]
	v_mfma_f32_16x16x32_bf16 v[70:73], v[168:171], v[236:239], v[70:73]
	v_mfma_f32_16x16x32_bf16 v[70:73], v[172:175], v[240:243], v[70:73]
	v_mfma_f32_16x16x32_bf16 v[74:77], v[144:147], v[236:239], v[74:77]
	v_mfma_f32_16x16x32_bf16 v[74:77], v[148:151], v[240:243], v[74:77]
	s_barrier
; #define PG8_STAGE(bufoff, gbase, voff) do { _Pragma("unroll") for (int _i = 0; _i < 2; ++_i) \
;         __builtin_amdgcn_global_load_lds((const unsigned*)((const char*)(gbase) + (voff)[_i]), (PG8_LAS unsigned*)(lds + (bufoff) + ldsw + _i * 8192), 16, 0, 0); } while (0)
; #define PG8_LDA(dst, b, h) do { _Pragma("unroll") for (int m = 0; m < 4; ++m) _Pragma("unroll") for (int k = 0; k < 2; ++k) dst[m][k] = *(const PG8_LAS bf16x8*)(lds + PG8_SA(b, h) + aoff + m * 2048 + k * 1024); } while (0)
; #define PG8_MMA(ai, bj, At, Bt) do { __builtin_amdgcn_s_setprio(1); _Pragma("unroll") for (int m = 0; m < 4; ++m) _Pragma("unroll") for (int n = 0; n < 2; ++n) _Pragma("unroll") for (int k = 0; k < 2; ++k) \
;         acc[ai][bj][m][n] = __builtin_amdgcn_mfma_f32_16x16x32_bf16(Bt[n][k], At[m][k], acc[ai][bj][m][n], 0, 0, 0); __builtin_amdgcn_s_setprio(0); } while (0)
; #define PG8_WAIT_V(n) asm volatile("s_waitcnt vmcnt(" #n ")" ::: "memory")
; #define PG8_WAIT_L(n) asm volatile("s_waitcnt lgkmcnt(" #n ")" ::: "memory")
; #define PG8_BAR __builtin_amdgcn_s_barrier()
; #define PG8_SCHED __builtin_amdgcn_sched_barrier(0)
; template <class Epi, class Sched, bool ALIGN_EPI = false, bool SP2 = false>
; __device__ __forceinline__ void gemm_phase(PG8_LAS unsigned char* lds, const Gemm g, const Sched& S, const Epi& E) {
;     ...
;         for (int t = 0; t < nt; t += 2) {
;     ...
;             PG8_LDA(At, 1, 1); PG8_STAGE(PG8_SB(1, 0), b3, voffB); PG8_STAGE(PG8_SB(1, 1), b3 + hstep, voffB); PG8_STAGE(PG8_SA(1, 0), a3, voffA);
;             PG8_WAIT_V(8); PG8_WAIT_L(0); PG8_BAR; PG8_MMA(1, 0, At, B0); PG8_MMA(1, 1, At, B1); PG8_BAR; PG8_SCHED;
	s_add_i32 s4, s4, s24
	v_lshl_add_u64 v[156:157], v[156:157], 0, s[28:29]
	s_mov_b32 m0, s4
	ds_read_b128 v[212:215], v155 offset:49152
	ds_read_b128 v[216:219], v155 offset:50176
	ds_read_b128 v[220:223], v155 offset:51200
	ds_read_b128 v[224:227], v155 offset:52224
	ds_read_b128 v[228:231], v155 offset:53248
	ds_read_b128 v[232:235], v155 offset:54272
	ds_read_b128 v[236:239], v155 offset:55296
	ds_read_b128 v[240:243], v155 offset:56320
	global_load_lds_dwordx4 v[156:157], off
	s_add_i32 m0, s4, 0x2000
	s_add_u32 s34, s54, 0x80080
	v_lshl_add_u64 v[156:157], v[192:193], 0, s[28:29]
	s_addc_u32 s35, s55, 0
	s_add_i32 s4, s5, s24
	global_load_lds_dwordx4 v[156:157], off
	v_lshl_add_u64 v[156:157], s[34:35], 0, v[4:5]
	s_mov_b32 m0, s4
	s_nop 0
	global_load_lds_dwordx4 v[156:157], off
	v_lshl_add_u64 v[156:157], s[34:35], 0, v[2:3]
	s_add_i32 m0, s4, 0x2000
	s_nop 0
	global_load_lds_dwordx4 v[156:157], off
	v_lshl_add_u64 v[156:157], v[244:245], 0, s[28:29]
	s_mov_b32 m0, s67
	s_nop 0
	global_load_lds_dwordx4 v[156:157], off
	v_lshl_add_u64 v[156:157], v[246:247], 0, s[28:29]
	s_mov_b32 m0, s72
	s_nop 0
	global_load_lds_dwordx4 v[156:157], off
	s_waitcnt vmcnt(8)
	s_waitcnt lgkmcnt(0)
	s_barrier
	v_mfma_f32_16x16x32_bf16 v[58:61], v[144:147], v[212:215], v[58:61]
	v_mfma_f32_16x16x32_bf16 v[58:61], v[148:151], v[216:219], v[58:61]
	v_mfma_f32_16x16x32_bf16 v[54:57], v[168:171], v[212:215], v[54:57]
	v_mfma_f32_16x16x32_bf16 v[54:57], v[172:175], v[216:219], v[54:57]
	v_mfma_f32_16x16x32_bf16 v[66:69], v[176:179], v[212:215], v[66:69]
	v_mfma_f32_16x16x32_bf16 v[66:69], v[180:183], v[216:219], v[66:69]
	v_mfma_f32_16x16x32_bf16 v[62:65], v[184:187], v[212:215], v[62:65]
	v_mfma_f32_16x16x32_bf16 v[62:65], v[188:191], v[216:219], v[62:65]
	v_mfma_f32_16x16x32_bf16 v[46:49], v[184:187], v[220:223], v[46:49]
	v_mfma_f32_16x16x32_bf16 v[46:49], v[188:191], v[224:227], v[46:49]
	v_mfma_f32_16x16x32_bf16 v[50:53], v[176:179], v[220:223], v[50:53]
	v_mfma_f32_16x16x32_bf16 v[50:53], v[180:183], v[224:227], v[50:53]
	v_mfma_f32_16x16x32_bf16 v[38:41], v[168:171], v[220:223], v[38:41]
	v_mfma_f32_16x16x32_bf16 v[38:41], v[172:175], v[224:227], v[38:41]
	v_mfma_f32_16x16x32_bf16 v[42:45], v[144:147], v[220:223], v[42:45]
	v_mfma_f32_16x16x32_bf16 v[42:45], v[148:151], v[224:227], v[42:45]
	v_mfma_f32_16x16x32_bf16 v[26:29], v[144:147], v[228:231], v[26:29]
	v_mfma_f32_16x16x32_bf16 v[26:29], v[148:151], v[232:235], v[26:29]
	v_mfma_f32_16x16x32_bf16 v[22:25], v[168:171], v[228:231], v[22:25]
	v_mfma_f32_16x16x32_bf16 v[22:25], v[172:175], v[232:235], v[22:25]
	v_mfma_f32_16x16x32_bf16 v[34:37], v[176:179], v[228:231], v[34:37]
	v_mfma_f32_16x16x32_bf16 v[34:37], v[180:183], v[232:235], v[34:37]
	v_mfma_f32_16x16x32_bf16 v[30:33], v[184:187], v[228:231], v[30:33]
	v_mfma_f32_16x16x32_bf16 v[30:33], v[188:191], v[232:235], v[30:33]
	v_mfma_f32_16x16x32_bf16 v[18:21], v[184:187], v[236:239], v[18:21]
	v_mfma_f32_16x16x32_bf16 v[18:21], v[188:191], v[240:243], v[18:21]
	v_mfma_f32_16x16x32_bf16 v[14:17], v[176:179], v[236:239], v[14:17]
	v_mfma_f32_16x16x32_bf16 v[14:17], v[180:183], v[240:243], v[14:17]
	v_mfma_f32_16x16x32_bf16 v[6:9], v[168:171], v[236:239], v[6:9]
	v_mfma_f32_16x16x32_bf16 v[6:9], v[172:175], v[240:243], v[6:9]
	v_mfma_f32_16x16x32_bf16 v[10:13], v[144:147], v[236:239], v[10:13]
	v_mfma_f32_16x16x32_bf16 v[10:13], v[148:151], v[240:243], v[10:13]
	s_barrier
	s_add_i32 s20, s20, 2
	s_add_u32 s56, s56, 0x100
	s_addc_u32 s57, s57, 0
	s_add_u32 s71, s71, 0x100
	s_addc_u32 s77, s77, 0
	s_cmp_gt_u32 s20, 29
	s_cbranch_scc0 .LBB0_387
	s_and_b64 vcc, exec, s[44:45]
	s_movk_i32 s75, 0x800
	s_movk_i32 s77, 0x6000
	s_mov_b32 s71, 0x44800000
	s_cbranch_vccz .LBB0_390
	s_barrier

; #define PG8_STAGE(bufoff, gbase, voff) do { _Pragma("unroll") for (int _i = 0; _i < 2; ++_i) \
;         __builtin_amdgcn_global_load_lds((const unsigned*)((const char*)(gbase) + (voff)[_i]), (PG8_LAS unsigned*)(lds + (bufoff) + ldsw + _i * 8192), 16, 0, 0); } while (0)
; #define PG8_LDA(dst, b, h) do { _Pragma("unroll") for (int m = 0; m < 4; ++m) _Pragma("unroll") for (int k = 0; k < 2; ++k) dst[m][k] = *(const PG8_LAS bf16x8*)(lds + PG8_SA(b, h) + aoff + m * 2048 + k * 1024); } while (0)
; #define PG8_LDB(dst, b, h) do { _Pragma("unroll") for (int n = 0; n < 2; ++n) _Pragma("unroll") for (int k = 0; k < 2; ++k) dst[n][k] = *(const PG8_LAS bf16x8*)(lds + PG8_SB(b, h) + boff + n * 2048 + k * 1024); } while (0)
; #define PG8_MMA(ai, bj, At, Bt) do { __builtin_amdgcn_s_setprio(1); _Pragma("unroll") for (int m = 0; m < 4; ++m) _Pragma("unroll") for (int n = 0; n < 2; ++n) _Pragma("unroll") for (int k = 0; k < 2; ++k) \
;         acc[ai][bj][m][n] = __builtin_amdgcn_mfma_f32_16x16x32_bf16(Bt[n][k], At[m][k], acc[ai][bj][m][n], 0, 0, 0); __builtin_amdgcn_s_setprio(0); } while (0)
; #define PG8_WAIT_V(n) asm volatile("s_waitcnt vmcnt(" #n ")" ::: "memory")
; #define PG8_BAR __builtin_amdgcn_s_barrier()
; template <class Epi, class Sched, bool ALIGN_EPI = false, bool SP2 = false>
; __device__ __forceinline__ void gemm_phase(PG8_LAS unsigned char* lds, const Gemm g, const Sched& S, const Epi& E) {
;     ...
;         for (int t = 0; t < nt; t += 2) {
;             const bool last = (t == nt - 2);
;             const char* a1 = cA + (size_t)(t + 1) * kstep;
;             const char* a2 = last ? nA : cA + (size_t)(t + 2) * kstep; const char* b2 = last ? nB : cB + (size_t)(t + 2) * kstep;
;             const char* a3 = a2 + kstep; const char* b3 = b2 + kstep;
;             if (last && has_next) S.a_ready(nxt);
;             if constexpr (SP2) {
;             PG8_LDB(B0, 0, 0); PG8_LDB(B1, 0, 1); PG8_SCHED; PG8_LDA(At, 0, 0); PG8_STAGE(PG8_SA(1, 1), a1 + hstep, voffA);
;             PG8_WAIT_V(8); PG8_WAIT_L(0); PG8_BAR; PG8_MMA(0, 0, At, B0); PG8_MMA(0, 1, At, B1); PG8_BAR; PG8_SCHED;
;             PG8_LDA(At, 0, 1); PG8_STAGE(PG8_SB(0, 0), b2, voffB); PG8_STAGE(PG8_SB(0, 1), b2 + hstep, voffB); PG8_STAGE(PG8_SA(0, 0), a2, voffA);
;             PG8_WAIT_V(8); PG8_WAIT_L(0); PG8_BAR; PG8_MMA(1, 0, At, B0); PG8_MMA(1, 1, At, B1); PG8_BAR; PG8_SCHED;
.LBB0_1738:
	s_add_u32 s4, s50, 0xfff80080
	s_addc_u32 s5, s51, -1
	s_add_i32 s6, 0, 0x10000
	s_cmp_eq_u32 s20, 28
	s_cselect_b32 s53, s43, s5
	s_cselect_b32 s52, s66, s4
	s_cselect_b32 s49, s45, s71
	s_cselect_b32 s48, s67, s69
	s_add_i32 s4, 0, 0x14000
	v_add_u32_e32 v146, s6, v158
	v_add_u32_e32 v180, s4, v158
	ds_read_b128 v[134:137], v146
	ds_read_b128 v[138:141], v146 offset:1024
	ds_read_b128 v[142:145], v146 offset:2048
	ds_read_b128 v[146:149], v146 offset:3072
	ds_read_b128 v[150:153], v180
	ds_read_b128 v[154:157], v180 offset:1024
	ds_read_b128 v[176:179], v180 offset:2048
	ds_read_b128 v[180:183], v180 offset:3072
	v_lshl_add_u64 v[234:235], s[50:51], 0, v[172:173]
	s_add_i32 m0, s54, 0xc000
	ds_read_b128 v[184:187], v188
	ds_read_b128 v[190:193], v188 offset:1024
	ds_read_b128 v[210:213], v188 offset:2048
	ds_read_b128 v[214:217], v188 offset:3072
	ds_read_b128 v[218:221], v188 offset:4096
	ds_read_b128 v[222:225], v188 offset:5120
	ds_read_b128 v[226:229], v188 offset:6144
	ds_read_b128 v[230:233], v188 offset:7168
	global_load_lds_dwordx4 v[234:235], off
	v_lshl_add_u64 v[234:235], s[50:51], 0, v[174:175]
	s_add_i32 m0, s54, 0xe000
	s_nop 0
	global_load_lds_dwordx4 v[234:235], off
	s_waitcnt vmcnt(8)
	s_waitcnt lgkmcnt(0)
	s_barrier
	v_mfma_f32_16x16x32_bf16 v[122:125], v[134:137], v[184:187], v[122:125]
	v_mfma_f32_16x16x32_bf16 v[122:125], v[138:141], v[190:193], v[122:125]
	v_mfma_f32_16x16x32_bf16 v[118:121], v[142:145], v[184:187], v[118:121]
	v_mfma_f32_16x16x32_bf16 v[118:121], v[146:149], v[190:193], v[118:121]
	v_mfma_f32_16x16x32_bf16 v[130:133], v[150:153], v[184:187], v[130:133]
	v_mfma_f32_16x16x32_bf16 v[130:133], v[154:157], v[190:193], v[130:133]
	v_mfma_f32_16x16x32_bf16 v[126:129], v[176:179], v[184:187], v[126:129]
	v_mfma_f32_16x16x32_bf16 v[126:129], v[180:183], v[190:193], v[126:129]
	v_mfma_f32_16x16x32_bf16 v[102:105], v[176:179], v[210:213], v[102:105]
	v_mfma_f32_16x16x32_bf16 v[102:105], v[180:183], v[214:217], v[102:105]
	v_mfma_f32_16x16x32_bf16 v[110:113], v[150:153], v[210:213], v[110:113]
	v_mfma_f32_16x16x32_bf16 v[110:113], v[154:157], v[214:217], v[110:113]
	v_mfma_f32_16x16x32_bf16 v[106:109], v[142:145], v[210:213], v[106:109]
	v_mfma_f32_16x16x32_bf16 v[106:109], v[146:149], v[214:217], v[106:109]
	v_mfma_f32_16x16x32_bf16 v[114:117], v[134:137], v[210:213], v[114:117]
	v_mfma_f32_16x16x32_bf16 v[114:117], v[138:141], v[214:217], v[114:117]
	v_mfma_f32_16x16x32_bf16 v[98:101], v[134:137], v[218:221], v[98:101]
	v_mfma_f32_16x16x32_bf16 v[98:101], v[138:141], v[222:225], v[98:101]
	v_mfma_f32_16x16x32_bf16 v[90:93], v[142:145], v[218:221], v[90:93]
	v_mfma_f32_16x16x32_bf16 v[90:93], v[146:149], v[222:225], v[90:93]
	v_mfma_f32_16x16x32_bf16 v[94:97], v[150:153], v[218:221], v[94:97]
	v_mfma_f32_16x16x32_bf16 v[94:97], v[154:157], v[222:225], v[94:97]
	v_mfma_f32_16x16x32_bf16 v[86:89], v[176:179], v[218:221], v[86:89]
	v_mfma_f32_16x16x32_bf16 v[86:89], v[180:183], v[222:225], v[86:89]
	v_mfma_f32_16x16x32_bf16 v[70:73], v[176:179], v[226:229], v[70:73]
	v_mfma_f32_16x16x32_bf16 v[70:73], v[180:183], v[230:233], v[70:73]
	v_mfma_f32_16x16x32_bf16 v[78:81], v[150:153], v[226:229], v[78:81]
	v_mfma_f32_16x16x32_bf16 v[78:81], v[154:157], v[230:233], v[78:81]
	v_mfma_f32_16x16x32_bf16 v[74:77], v[142:145], v[226:229], v[74:77]
	v_mfma_f32_16x16x32_bf16 v[74:77], v[146:149], v[230:233], v[74:77]
	v_mfma_f32_16x16x32_bf16 v[82:85], v[134:137], v[226:229], v[82:85]
	v_mfma_f32_16x16x32_bf16 v[82:85], v[138:141], v[230:233], v[82:85]
	s_barrier
	s_add_i32 s5, s6, s24
	v_lshl_add_u64 v[234:235], s[48:49], 0, v[4:5]
	s_mov_b32 m0, s5
	ds_read_b128 v[184:187], v188 offset:16384
	ds_read_b128 v[190:193], v188 offset:17408
	ds_read_b128 v[210:213], v188 offset:18432
	ds_read_b128 v[214:217], v188 offset:19456
	ds_read_b128 v[218:221], v188 offset:20480
	ds_read_b128 v[222:225], v188 offset:21504
	ds_read_b128 v[226:229], v188 offset:22528
	ds_read_b128 v[230:233], v188 offset:23552
	global_load_lds_dwordx4 v[234:235], off
	s_add_i32 m0, s5, 0x2000
	s_add_u32 s34, s48, 0x80000
	v_lshl_add_u64 v[236:237], s[48:49], 0, v[2:3]
	s_addc_u32 s35, s49, 0
	s_add_i32 s4, s4, s24
	global_load_lds_dwordx4 v[236:237], off
	v_lshl_add_u64 v[238:239], s[34:35], 0, v[4:5]
	s_mov_b32 m0, s4
	v_lshl_add_u64 v[240:241], s[52:53], 0, v[168:169]
	global_load_lds_dwordx4 v[238:239], off
	v_lshl_add_u64 v[238:239], s[34:35], 0, v[2:3]
	s_add_i32 m0, s4, 0x2000
	s_nop 0
	global_load_lds_dwordx4 v[238:239], off
	v_lshl_add_u64 v[238:239], s[52:53], 0, v[170:171]
	s_mov_b32 m0, s54
	s_nop 0
	global_load_lds_dwordx4 v[238:239], off
	s_mov_b32 m0, s55
	s_nop 0
	global_load_lds_dwordx4 v[240:241], off
	s_waitcnt vmcnt(8)
	s_waitcnt lgkmcnt(0)
	s_barrier
; #define PG8_STAGE(bufoff, gbase, voff) do { _Pragma("unroll") for (int _i = 0; _i < 2; ++_i) \
;         __builtin_amdgcn_global_load_lds((const unsigned*)((const char*)(gbase) + (voff)[_i]), (PG8_LAS unsigned*)(lds + (bufoff) + ldsw + _i * 8192), 16, 0, 0); } while (0)
; #define PG8_LDA(dst, b, h) do { _Pragma("unroll") for (int m = 0; m < 4; ++m) _Pragma("unroll") for (int k = 0; k < 2; ++k) dst[m][k] = *(const PG8_LAS bf16x8*)(lds + PG8_SA(b, h) + aoff + m * 2048 + k * 1024); } while (0)
; #define PG8_LDB(dst, b, h) do { _Pragma("unroll") for (int n = 0; n < 2; ++n) _Pragma("unroll") for (int k = 0; k < 2; ++k) dst[n][k] = *(const PG8_LAS bf16x8*)(lds + PG8_SB(b, h) + boff + n * 2048 + k * 1024); } while (0)
; #define PG8_MMA(ai, bj, At, Bt) do { __builtin_amdgcn_s_setprio(1); _Pragma("unroll") for (int m = 0; m < 4; ++m) _Pragma("unroll") for (int n = 0; n < 2; ++n) _Pragma("unroll") for (int k = 0; k < 2; ++k) \
;         acc[ai][bj][m][n] = __builtin_amdgcn_mfma_f32_16x16x32_bf16(Bt[n][k], At[m][k], acc[ai][bj][m][n], 0, 0, 0); __builtin_amdgcn_s_setprio(0); } while (0)
; #define PG8_WAIT_V(n) asm volatile("s_waitcnt vmcnt(" #n ")" ::: "memory")
; #define PG8_WAIT_L(n) asm volatile("s_waitcnt lgkmcnt(" #n ")" ::: "memory")
; #define PG8_BAR __builtin_amdgcn_s_barrier()
; #define PG8_SCHED __builtin_amdgcn_sched_barrier(0)
; template <class Epi, class Sched, bool ALIGN_EPI = false, bool SP2 = false>
; __device__ __forceinline__ void gemm_phase(PG8_LAS unsigned char* lds, const Gemm g, const Sched& S, const Epi& E) {
;     ...
;             PG8_WAIT_V(8); PG8_WAIT_L(0); PG8_BAR; PG8_MMA(1, 0, At, B0); PG8_MMA(1, 1, At, B1); PG8_BAR; PG8_SCHED;
;             PG8_LDB(B0, 1, 0); PG8_LDB(B1, 1, 1); PG8_SCHED; PG8_LDA(At, 1, 0); PG8_STAGE(PG8_SA(0, 1), a2 + hstep, voffA);
;             PG8_WAIT_V(8); PG8_WAIT_L(0); PG8_BAR; PG8_MMA(0, 0, At, B0); PG8_MMA(0, 1, At, B1); PG8_BAR; PG8_SCHED;
	v_mfma_f32_16x16x32_bf16 v[58:61], v[134:137], v[184:187], v[58:61]
	v_mfma_f32_16x16x32_bf16 v[58:61], v[138:141], v[190:193], v[58:61]
	v_mfma_f32_16x16x32_bf16 v[54:57], v[142:145], v[184:187], v[54:57]
	v_mfma_f32_16x16x32_bf16 v[54:57], v[146:149], v[190:193], v[54:57]
	v_mfma_f32_16x16x32_bf16 v[66:69], v[150:153], v[184:187], v[66:69]
	v_mfma_f32_16x16x32_bf16 v[66:69], v[154:157], v[190:193], v[66:69]
	v_mfma_f32_16x16x32_bf16 v[62:65], v[176:179], v[184:187], v[62:65]
	v_mfma_f32_16x16x32_bf16 v[62:65], v[180:183], v[190:193], v[62:65]
	v_mfma_f32_16x16x32_bf16 v[38:41], v[176:179], v[210:213], v[38:41]
	v_mfma_f32_16x16x32_bf16 v[38:41], v[180:183], v[214:217], v[38:41]
	v_mfma_f32_16x16x32_bf16 v[46:49], v[150:153], v[210:213], v[46:49]
	v_mfma_f32_16x16x32_bf16 v[46:49], v[154:157], v[214:217], v[46:49]
	v_mfma_f32_16x16x32_bf16 v[42:45], v[142:145], v[210:213], v[42:45]
	v_mfma_f32_16x16x32_bf16 v[42:45], v[146:149], v[214:217], v[42:45]
	v_mfma_f32_16x16x32_bf16 v[50:53], v[134:137], v[210:213], v[50:53]
	v_mfma_f32_16x16x32_bf16 v[50:53], v[138:141], v[214:217], v[50:53]
	v_mfma_f32_16x16x32_bf16 v[34:37], v[134:137], v[218:221], v[34:37]
	v_mfma_f32_16x16x32_bf16 v[34:37], v[138:141], v[222:225], v[34:37]
	v_mfma_f32_16x16x32_bf16 v[26:29], v[142:145], v[218:221], v[26:29]
	v_mfma_f32_16x16x32_bf16 v[26:29], v[146:149], v[222:225], v[26:29]
	v_mfma_f32_16x16x32_bf16 v[30:33], v[150:153], v[218:221], v[30:33]
	v_mfma_f32_16x16x32_bf16 v[30:33], v[154:157], v[222:225], v[30:33]
	v_mfma_f32_16x16x32_bf16 v[22:25], v[176:179], v[218:221], v[22:25]
	v_mfma_f32_16x16x32_bf16 v[22:25], v[180:183], v[222:225], v[22:25]
	v_mfma_f32_16x16x32_bf16 v[6:9], v[176:179], v[226:229], v[6:9]
	v_mfma_f32_16x16x32_bf16 v[6:9], v[180:183], v[230:233], v[6:9]
	v_mfma_f32_16x16x32_bf16 v[14:17], v[150:153], v[226:229], v[14:17]
	v_mfma_f32_16x16x32_bf16 v[14:17], v[154:157], v[230:233], v[14:17]
	v_mfma_f32_16x16x32_bf16 v[10:13], v[142:145], v[226:229], v[10:13]
	v_mfma_f32_16x16x32_bf16 v[10:13], v[146:149], v[230:233], v[10:13]
	v_mfma_f32_16x16x32_bf16 v[18:21], v[134:137], v[226:229], v[18:21]
	v_mfma_f32_16x16x32_bf16 v[18:21], v[138:141], v[230:233], v[18:21]
	s_barrier
	s_add_i32 s4, 0, 0x18000
	s_add_i32 s5, 0, 0x1c000
	v_add_u32_e32 v146, s4, v158
	v_add_u32_e32 v180, s5, v158
	ds_read_b128 v[134:137], v146
	ds_read_b128 v[138:141], v146 offset:1024
	ds_read_b128 v[142:145], v146 offset:2048
	ds_read_b128 v[146:149], v146 offset:3072
	ds_read_b128 v[150:153], v180
	ds_read_b128 v[154:157], v180 offset:1024
	ds_read_b128 v[176:179], v180 offset:2048
	ds_read_b128 v[180:183], v180 offset:3072
	s_add_u32 s34, s52, 0x80000
	s_addc_u32 s35, s53, 0
	s_mov_b32 m0, s56
	v_lshl_add_u64 v[242:243], s[34:35], 0, v[170:171]
	ds_read_b128 v[184:187], v188 offset:32768
	ds_read_b128 v[190:193], v188 offset:33792
	ds_read_b128 v[210:213], v188 offset:34816
	ds_read_b128 v[214:217], v188 offset:35840
	ds_read_b128 v[218:221], v188 offset:36864
	ds_read_b128 v[222:225], v188 offset:37888
	ds_read_b128 v[226:229], v188 offset:38912
	ds_read_b128 v[230:233], v188 offset:39936
	global_load_lds_dwordx4 v[242:243], off
	v_lshl_add_u64 v[242:243], s[34:35], 0, v[168:169]
	s_mov_b32 m0, s57
	s_nop 0
	global_load_lds_dwordx4 v[242:243], off
	s_waitcnt vmcnt(8)
	s_waitcnt lgkmcnt(0)
	s_barrier
	v_mfma_f32_16x16x32_bf16 v[122:125], v[134:137], v[184:187], v[122:125]
	v_mfma_f32_16x16x32_bf16 v[122:125], v[138:141], v[190:193], v[122:125]
	v_mfma_f32_16x16x32_bf16 v[118:121], v[142:145], v[184:187], v[118:121]
	v_mfma_f32_16x16x32_bf16 v[118:121], v[146:149], v[190:193], v[118:121]
	v_mfma_f32_16x16x32_bf16 v[130:133], v[150:153], v[184:187], v[130:133]
	v_mfma_f32_16x16x32_bf16 v[130:133], v[154:157], v[190:193], v[130:133]
	v_mfma_f32_16x16x32_bf16 v[126:129], v[176:179], v[184:187], v[126:129]
	v_mfma_f32_16x16x32_bf16 v[126:129], v[180:183], v[190:193], v[126:129]
	v_mfma_f32_16x16x32_bf16 v[102:105], v[176:179], v[210:213], v[102:105]
	v_mfma_f32_16x16x32_bf16 v[102:105], v[180:183], v[214:217], v[102:105]
	v_mfma_f32_16x16x32_bf16 v[110:113], v[150:153], v[210:213], v[110:113]
	v_mfma_f32_16x16x32_bf16 v[110:113], v[154:157], v[214:217], v[110:113]
	v_mfma_f32_16x16x32_bf16 v[106:109], v[142:145], v[210:213], v[106:109]
	v_mfma_f32_16x16x32_bf16 v[106:109], v[146:149], v[214:217], v[106:109]
	v_mfma_f32_16x16x32_bf16 v[114:117], v[134:137], v[210:213], v[114:117]
	v_mfma_f32_16x16x32_bf16 v[114:117], v[138:141], v[214:217], v[114:117]
	v_mfma_f32_16x16x32_bf16 v[98:101], v[134:137], v[218:221], v[98:101]
	v_mfma_f32_16x16x32_bf16 v[98:101], v[138:141], v[222:225], v[98:101]
	v_mfma_f32_16x16x32_bf16 v[90:93], v[142:145], v[218:221], v[90:93]
	v_mfma_f32_16x16x32_bf16 v[90:93], v[146:149], v[222:225], v[90:93]
	v_mfma_f32_16x16x32_bf16 v[94:97], v[150:153], v[218:221], v[94:97]
	v_mfma_f32_16x16x32_bf16 v[94:97], v[154:157], v[222:225], v[94:97]
	v_mfma_f32_16x16x32_bf16 v[86:89], v[176:179], v[218:221], v[86:89]
	v_mfma_f32_16x16x32_bf16 v[86:89], v[180:183], v[222:225], v[86:89]
	v_mfma_f32_16x16x32_bf16 v[70:73], v[176:179], v[226:229], v[70:73]
	v_mfma_f32_16x16x32_bf16 v[70:73], v[180:183], v[230:233], v[70:73]
	v_mfma_f32_16x16x32_bf16 v[78:81], v[150:153], v[226:229], v[78:81]
	v_mfma_f32_16x16x32_bf16 v[78:81], v[154:157], v[230:233], v[78:81]
	v_mfma_f32_16x16x32_bf16 v[74:77], v[142:145], v[226:229], v[74:77]
	v_mfma_f32_16x16x32_bf16 v[74:77], v[146:149], v[230:233], v[74:77]
	v_mfma_f32_16x16x32_bf16 v[82:85], v[134:137], v[226:229], v[82:85]
	v_mfma_f32_16x16x32_bf16 v[82:85], v[138:141], v[230:233], v[82:85]
	s_barrier
; #define PG8_STAGE(bufoff, gbase, voff) do { _Pragma("unroll") for (int _i = 0; _i < 2; ++_i) \
;         __builtin_amdgcn_global_load_lds((const unsigned*)((const char*)(gbase) + (voff)[_i]), (PG8_LAS unsigned*)(lds + (bufoff) + ldsw + _i * 8192), 16, 0, 0); } while (0)
; #define PG8_LDA(dst, b, h) do { _Pragma("unroll") for (int m = 0; m < 4; ++m) _Pragma("unroll") for (int k = 0; k < 2; ++k) dst[m][k] = *(const PG8_LAS bf16x8*)(lds + PG8_SA(b, h) + aoff + m * 2048 + k * 1024); } while (0)
; #define PG8_MMA(ai, bj, At, Bt) do { __builtin_amdgcn_s_setprio(1); _Pragma("unroll") for (int m = 0; m < 4; ++m) _Pragma("unroll") for (int n = 0; n < 2; ++n) _Pragma("unroll") for (int k = 0; k < 2; ++k) \
;         acc[ai][bj][m][n] = __builtin_amdgcn_mfma_f32_16x16x32_bf16(Bt[n][k], At[m][k], acc[ai][bj][m][n], 0, 0, 0); __builtin_amdgcn_s_setprio(0); } while (0)
; #define PG8_WAIT_V(n) asm volatile("s_waitcnt vmcnt(" #n ")" ::: "memory")
; #define PG8_WAIT_L(n) asm volatile("s_waitcnt lgkmcnt(" #n ")" ::: "memory")
; #define PG8_BAR __builtin_amdgcn_s_barrier()
; #define PG8_SCHED __builtin_amdgcn_sched_barrier(0)
; template <class Epi, class Sched, bool ALIGN_EPI = false, bool SP2 = false>
; __device__ __forceinline__ void gemm_phase(PG8_LAS unsigned char* lds, const Gemm g, const Sched& S, const Epi& E) {
;     ...
;         for (int t = 0; t < nt; t += 2) {
;     ...
;             PG8_LDA(At, 1, 1); PG8_STAGE(PG8_SB(1, 0), b3, voffB); PG8_STAGE(PG8_SB(1, 1), b3 + hstep, voffB); PG8_STAGE(PG8_SA(1, 0), a3, voffA);
;             PG8_WAIT_V(8); PG8_WAIT_L(0); PG8_BAR; PG8_MMA(1, 0, At, B0); PG8_MMA(1, 1, At, B1); PG8_BAR; PG8_SCHED;
;     ...
;         if constexpr (ALIGN_EPI) { if (wr == 0) PG8_BAR; }
	s_add_i32 s4, s4, s24
	v_lshl_add_u64 v[234:235], v[234:235], 0, s[28:29]
	s_mov_b32 m0, s4
	ds_read_b128 v[184:187], v188 offset:49152
	ds_read_b128 v[190:193], v188 offset:50176
	ds_read_b128 v[210:213], v188 offset:51200
	ds_read_b128 v[214:217], v188 offset:52224
	ds_read_b128 v[218:221], v188 offset:53248
	ds_read_b128 v[222:225], v188 offset:54272
	ds_read_b128 v[226:229], v188 offset:55296
	ds_read_b128 v[230:233], v188 offset:56320
	global_load_lds_dwordx4 v[234:235], off
	s_add_i32 m0, s4, 0x2000
	s_add_u32 s34, s48, 0x80080
	v_lshl_add_u64 v[234:235], v[236:237], 0, s[28:29]
	s_addc_u32 s35, s49, 0
	s_add_i32 s4, s5, s24
	global_load_lds_dwordx4 v[234:235], off
	v_lshl_add_u64 v[234:235], s[34:35], 0, v[4:5]
	s_mov_b32 m0, s4
	s_nop 0
	global_load_lds_dwordx4 v[234:235], off
	v_lshl_add_u64 v[234:235], s[34:35], 0, v[2:3]
	s_add_i32 m0, s4, 0x2000
	s_nop 0
	global_load_lds_dwordx4 v[234:235], off
	v_lshl_add_u64 v[234:235], v[238:239], 0, s[28:29]
	s_mov_b32 m0, s60
	s_nop 0
	global_load_lds_dwordx4 v[234:235], off
	v_lshl_add_u64 v[234:235], v[240:241], 0, s[28:29]
	s_mov_b32 m0, s61
	s_nop 0
	global_load_lds_dwordx4 v[234:235], off
	s_waitcnt vmcnt(8)
	s_waitcnt lgkmcnt(0)
	s_barrier
	v_mfma_f32_16x16x32_bf16 v[58:61], v[134:137], v[184:187], v[58:61]
	v_mfma_f32_16x16x32_bf16 v[58:61], v[138:141], v[190:193], v[58:61]
	v_mfma_f32_16x16x32_bf16 v[54:57], v[142:145], v[184:187], v[54:57]
	v_mfma_f32_16x16x32_bf16 v[54:57], v[146:149], v[190:193], v[54:57]
	v_mfma_f32_16x16x32_bf16 v[66:69], v[150:153], v[184:187], v[66:69]
	v_mfma_f32_16x16x32_bf16 v[66:69], v[154:157], v[190:193], v[66:69]
	v_mfma_f32_16x16x32_bf16 v[62:65], v[176:179], v[184:187], v[62:65]
	v_mfma_f32_16x16x32_bf16 v[62:65], v[180:183], v[190:193], v[62:65]
	v_mfma_f32_16x16x32_bf16 v[38:41], v[176:179], v[210:213], v[38:41]
	v_mfma_f32_16x16x32_bf16 v[38:41], v[180:183], v[214:217], v[38:41]
	v_mfma_f32_16x16x32_bf16 v[46:49], v[150:153], v[210:213], v[46:49]
	v_mfma_f32_16x16x32_bf16 v[46:49], v[154:157], v[214:217], v[46:49]
	v_mfma_f32_16x16x32_bf16 v[42:45], v[142:145], v[210:213], v[42:45]
	v_mfma_f32_16x16x32_bf16 v[42:45], v[146:149], v[214:217], v[42:45]
	v_mfma_f32_16x16x32_bf16 v[50:53], v[134:137], v[210:213], v[50:53]
	v_mfma_f32_16x16x32_bf16 v[50:53], v[138:141], v[214:217], v[50:53]
	v_mfma_f32_16x16x32_bf16 v[34:37], v[134:137], v[218:221], v[34:37]
	v_mfma_f32_16x16x32_bf16 v[34:37], v[138:141], v[222:225], v[34:37]
	v_mfma_f32_16x16x32_bf16 v[26:29], v[142:145], v[218:221], v[26:29]
	v_mfma_f32_16x16x32_bf16 v[26:29], v[146:149], v[222:225], v[26:29]
	v_mfma_f32_16x16x32_bf16 v[30:33], v[150:153], v[218:221], v[30:33]
	v_mfma_f32_16x16x32_bf16 v[30:33], v[154:157], v[222:225], v[30:33]
	v_mfma_f32_16x16x32_bf16 v[22:25], v[176:179], v[218:221], v[22:25]
	v_mfma_f32_16x16x32_bf16 v[22:25], v[180:183], v[222:225], v[22:25]
	v_mfma_f32_16x16x32_bf16 v[6:9], v[176:179], v[226:229], v[6:9]
	v_mfma_f32_16x16x32_bf16 v[6:9], v[180:183], v[230:233], v[6:9]
	v_mfma_f32_16x16x32_bf16 v[14:17], v[150:153], v[226:229], v[14:17]
	v_mfma_f32_16x16x32_bf16 v[14:17], v[154:157], v[230:233], v[14:17]
	v_mfma_f32_16x16x32_bf16 v[10:13], v[142:145], v[226:229], v[10:13]
	v_mfma_f32_16x16x32_bf16 v[10:13], v[146:149], v[230:233], v[10:13]
	v_mfma_f32_16x16x32_bf16 v[18:21], v[134:137], v[226:229], v[18:21]
	v_mfma_f32_16x16x32_bf16 v[18:21], v[138:141], v[230:233], v[18:21]
	s_barrier
	s_add_i32 s20, s20, 2
	s_add_u32 s50, s50, 0x100
	s_addc_u32 s51, s51, 0
	s_add_u32 s69, s69, 0x100
	s_addc_u32 s71, s71, 0
	s_cmp_gt_u32 s20, 29
	s_cbranch_scc0 .LBB0_1738
	s_and_b64 vcc, exec, s[40:41]
	s_cbranch_vccz .LBB0_1741
	s_barrier
